# RG-LRU gate blocks: 11-12 bias/softplus f32x4 loads per direction prefetched with the weight fragments (pass 1 and 3)
# speedup vs baseline: 1.0084x; 1.0084x over previous
.LBB0_355:
	s_or_b64 exec, exec, s[8:9]
	v_mov_b32_e32 v161, v191
	s_waitcnt lgkmcnt(0)
	s_barrier
	v_mov_b32_e32 v162, v191
	v_and_b32_e32 v168, 15, v161
	v_lshrrev_b32_e32 v169, 4, v161
	v_bfe_u32 v170, v161, 4, 2
	s_mov_b64 s[2:3], s[74:75]
	v_bfe_u32 v163, v161, 1, 3
	v_ashrrev_i32_e32 v141, 6, v161
	v_lshlrev_b32_e32 v142, 7, v168
	v_bitop3_b32 v8, v169, v163, 3 bitop3:0x6c
	v_bitop3_b32 v13, v170, v163, 4 bitop3:0x36
	v_lshl_or_b32 v12, v141, 11, v142
	v_lshlrev_b32_e32 v8, 4, v8
	v_lshlrev_b32_e32 v13, 4, v13
	s_add_u32 s2, s2, s29
	v_add3_u32 v8, s60, v8, v12
	v_add3_u32 v12, s60, v13, v12
	s_addc_u32 s3, s3, 0
	v_lshlrev_b32_e32 v144, 4, v170
	ds_read_b128 v[8:11], v8
	ds_read_b128 v[72:75], v12
	v_lshl_add_u64 v[12:13], s[2:3], 0, v[144:145]
	s_mov_b64 s[2:3], 0x3980000
	v_lshl_add_u64 v[164:165], v[12:13], 0, s[2:3]
	s_mov_b64 s[2:3], 0x39a0000
	v_mov_b32_e32 v143, v145
	v_lshl_add_u64 v[166:167], v[12:13], 0, s[2:3]
	v_lshl_add_u64 v[60:61], v[164:165], 0, v[142:143]
	v_lshl_add_u64 v[62:63], v[166:167], 0, v[142:143]
	flat_load_dwordx4 v[12:15], v[60:61]
	flat_load_dwordx4 v[48:51], v[62:63]
	flat_load_dwordx4 v[52:55], v[60:61] offset:64
	flat_load_dwordx4 v[56:59], v[62:63] offset:64
	v_lshrrev_b32_e32 v172, 1, v161
	v_readlane_b32 s40, v254, 22
	v_readlane_b32 s44, v254, 26
	v_readlane_b32 s45, v254, 27
	s_mov_b64 s[2:3], s[44:45]
	v_readlane_b32 s48, v254, 30
	v_readlane_b32 s49, v254, 31
	s_mov_b64 s[8:9], s[48:49]
	s_mov_b32 s37, 0x122e6000
	s_mov_b32 s38, 0xc1000000
	v_readlane_b32 s41, v254, 23
	v_readlane_b32 s42, v254, 24
	v_readlane_b32 s43, v254, 25
	v_readlane_b32 s46, v254, 28
	v_readlane_b32 s47, v254, 29
	v_readlane_b32 s50, v254, 32
	v_readlane_b32 s51, v254, 33
	v_readlane_b32 s52, v254, 34
	v_readlane_b32 s53, v254, 35
	v_readlane_b32 s54, v254, 36
	v_readlane_b32 s55, v254, 37
	s_waitcnt vmcnt(0) lgkmcnt(0)
	v_mfma_f32_16x16x32_bf16 v[12:15], v[12:15], v[8:11], 0
	v_mfma_f32_16x16x32_bf16 v[48:51], v[48:51], v[8:11], 0
	v_mfma_f32_16x16x32_bf16 v[68:71], v[52:55], v[72:75], v[12:15]
	v_mfma_f32_16x16x32_bf16 v[64:67], v[56:59], v[72:75], v[48:51]
	s_nop 4
	flat_load_dwordx4 v[12:15], v[60:61] offset:2048
	flat_load_dwordx4 v[48:51], v[62:63] offset:2048
	flat_load_dwordx4 v[52:55], v[60:61] offset:2112
	flat_load_dwordx4 v[56:59], v[62:63] offset:2112
	s_waitcnt vmcnt(0) lgkmcnt(0)
	v_mfma_f32_16x16x32_bf16 v[12:15], v[12:15], v[8:11], 0
	v_mfma_f32_16x16x32_bf16 v[48:51], v[48:51], v[8:11], 0
	v_mfma_f32_16x16x32_bf16 v[60:63], v[52:55], v[72:75], v[12:15]
	s_nop 5
	v_or_b32_e32 v12, 0x1000, v142
	v_mov_b32_e32 v13, v145
	v_lshl_add_u64 v[52:53], v[164:165], 0, v[12:13]
	v_mfma_f32_16x16x32_bf16 v[56:59], v[56:59], v[72:75], v[48:51]
	v_lshl_add_u64 v[146:147], v[166:167], 0, v[12:13]
	flat_load_dwordx4 v[12:15], v[52:53]
	s_nop 0
	flat_load_dwordx4 v[48:51], v[146:147]
	s_nop 0
	flat_load_dwordx4 v[52:55], v[52:53] offset:64
	s_nop 0
	flat_load_dwordx4 v[146:149], v[146:147] offset:64
	s_waitcnt vmcnt(0) lgkmcnt(0)
	v_mfma_f32_16x16x32_bf16 v[12:15], v[12:15], v[8:11], 0
	v_mfma_f32_16x16x32_bf16 v[48:51], v[48:51], v[8:11], 0
	v_mfma_f32_16x16x32_bf16 v[52:55], v[52:55], v[72:75], v[12:15]
	s_nop 5
	v_or_b32_e32 v12, 0x1800, v142
	v_mov_b32_e32 v13, v145
	v_lshl_add_u64 v[142:143], v[164:165], 0, v[12:13]
	v_mfma_f32_16x16x32_bf16 v[48:51], v[146:149], v[72:75], v[48:51]
	v_lshl_add_u64 v[164:165], v[166:167], 0, v[12:13]
	flat_load_dwordx4 v[12:15], v[142:143]
	flat_load_dwordx4 v[146:149], v[164:165]
	s_waitcnt vmcnt(0) lgkmcnt(0)
	v_mfma_f32_16x16x32_bf16 v[12:15], v[12:15], v[8:11], 0
	v_mfma_f32_16x16x32_bf16 v[8:11], v[146:149], v[8:11], 0
	flat_load_dwordx4 v[146:149], v[142:143] offset:64
	s_nop 0
	flat_load_dwordx4 v[164:167], v[164:165] offset:64
	v_lshlrev_b32_e32 v142, 2, v170
	v_mov_b32_e32 v143, v145
	v_or_b32_e32 v180, s22, v142
	v_ashrrev_i32_e32 v181, 31, v180
	v_lshlrev_b64 v[180:181], 2, v[180:181]
	s_add_u32 s98, s74, s30
	s_addc_u32 s99, s75, 0
	s_add_u32 s98, s98, 0x122e6000
	s_addc_u32 s99, s99, 0
	v_lshl_add_u64 v[184:185], s[98:99], 0, v[144:145]
	v_lshl_add_u64 v[178:179], s[44:45], 0, v[180:181]
	v_lshl_add_u64 v[182:183], s[48:49], 0, v[180:181]
	global_load_dwordx4 v[216:219], v[178:179], off
	global_load_dwordx4 v[220:223], v[182:183], off
	global_load_dwordx4 v[224:227], v[184:185], off
	global_load_dwordx4 v[228:231], v[178:179], off offset:64
	global_load_dwordx4 v[232:235], v[182:183], off offset:64
	global_load_dwordx4 v[236:239], v[184:185], off offset:64
	global_load_dwordx4 v[240:243], v[178:179], off offset:128
	global_load_dwordx4 v[244:247], v[182:183], off offset:128
	global_load_dwordx4 v[248:251], v[184:185], off offset:128
	global_load_dwordx4 v[178:181], v[178:179], off offset:192
	global_load_dwordx4 v[182:185], v[182:183], off offset:192
	s_waitcnt vmcnt(0) lgkmcnt(0)
	v_mfma_f32_16x16x32_bf16 v[12:15], v[146:149], v[72:75], v[12:15]
	v_mfma_f32_16x16x32_bf16 v[8:11], v[164:167], v[72:75], v[8:11]
	v_lshl_or_b32 v72, v141, 4, v168
	v_lshlrev_b32_e32 v164, 7, v72
	v_and_b32_e32 v73, 8, v172
	v_lshlrev_b32_e32 v167, 8, v72
	v_or_b32_e32 v72, s22, v142
	v_add_u32_e32 v166, s60, v73
	v_ashrrev_i32_e32 v73, 31, v72
	v_lshlrev_b64 v[146:147], 2, v[72:73]
	v_lshl_add_u64 v[72:73], s[2:3], 0, v[146:147]
	s_mov_b64 s[2:3], s[74:75]
	v_lshl_add_u64 v[146:147], s[8:9], 0, v[146:147]
	s_add_u32 s2, s2, s30
	s_addc_u32 s3, s3, 0
	v_bfe_u32 v165, v169, 1, 1
	v_lshl_add_u64 v[168:169], s[2:3], 0, v[144:145]
	v_add_co_u32_e64 v168, s[8:9], s37, v168
	v_bitop3_b32 v172, v165, v172, 7 bitop3:0x78
	s_nop 0
	v_addc_co_u32_e64 v169, s[8:9], 0, v169, s[8:9]
	v_lshlrev_b32_e32 v172, 4, v172
	v_add3_u32 v172, v166, v172, v164
	ds_read_b64 v[172:173], v172
	s_mov_b64 s[2:3], s[44:45]
	s_waitcnt lgkmcnt(0)
	v_lshlrev_b32_e32 v174, 16, v172
	v_and_b32_e32 v175, 0xffff0000, v172
	v_lshlrev_b32_e32 v172, 16, v173
	v_and_b32_e32 v173, 0xffff0000, v173
	v_add_f32_e32 v68, v68, v216
	v_add_f32_e32 v69, v69, v217
	v_mul_f32_e32 v68, 0xbfb8aa3b, v68
	v_mul_f32_e32 v69, 0xbfb8aa3b, v69
	v_exp_f32_e32 v68, v68
	v_exp_f32_e32 v69, v69
	v_add_f32_e32 v64, v64, v220
	v_add_f32_e32 v65, v65, v221
	v_add_f32_e32 v68, 1.0, v68
	v_add_f32_e32 v69, 1.0, v69
	v_rcp_f32_e32 v68, v68
	v_rcp_f32_e32 v69, v69
	v_add_f32_e32 v70, v70, v218
	v_add_f32_e32 v71, v71, v219
	v_mul_f32_e32 v70, 0xbfb8aa3b, v70
	v_pk_mul_f32 v[68:69], v[68:69], s[38:39] op_sel_hi:[1,0]
	v_mul_f32_e32 v71, 0xbfb8aa3b, v71
	v_pk_mul_f32 v[72:73], v[224:225], v[68:69]
	v_exp_f32_e32 v70, v70
	v_pk_add_f32 v[146:147], v[72:73], v[72:73]
	v_mul_f32_e32 v68, 0x3fb8aa3b, v72
	v_fmamk_f32 v69, v146, 0x3ab60b61, v195
	v_exp_f32_e32 v68, v68
	v_fmaak_f32 v69, v146, v69, 0x3d2aaaab
	v_fmaak_f32 v69, v146, v69, 0x3e2aaaab
	v_exp_f32_e32 v71, v71
	v_fma_f32 v69, v146, v69, 0.5
	v_fma_f32 v69, v146, v69, 1.0
	v_mul_f32_e64 v69, v69, -v146
	v_fma_f32 v72, -v68, v68, 1.0
	v_cmp_lt_f32_e64 s[12:13], s84, v146
	v_add_f32_e32 v70, 1.0, v70
	v_add_f32_e32 v71, 1.0, v71
	v_cndmask_b32_e64 v69, v72, v69, s[12:13]
	v_sqrt_f32_e32 v72, v69
	v_mul_f32_e32 v69, 0x3fb8aa3b, v73
	v_fmamk_f32 v73, v147, 0x3ab60b61, v195
	v_rcp_f32_e32 v70, v70
	v_rcp_f32_e32 v71, v71
	v_exp_f32_e32 v69, v69
	v_fmaak_f32 v73, v147, v73, 0x3d2aaaab
	v_fmaak_f32 v73, v147, v73, 0x3e2aaaab
	v_fma_f32 v73, v147, v73, 0.5
	v_fma_f32 v73, v147, v73, 1.0
	v_pk_mul_f32 v[70:71], v[70:71], s[38:39] op_sel_hi:[1,0]
	v_cmp_lt_f32_e64 s[8:9], s84, v147
	v_mul_f32_e64 v73, v73, -v147
	v_fma_f32 v146, -v69, v69, 1.0
	v_pk_mul_f32 v[74:75], v[226:227], v[70:71]
	v_cndmask_b32_e64 v73, v146, v73, s[8:9]
	v_pk_add_f32 v[146:147], v[74:75], v[74:75]
	v_mul_f32_e32 v70, 0x3fb8aa3b, v74
	v_fmamk_f32 v71, v146, 0x3ab60b61, v195
	v_exp_f32_e32 v70, v70
	v_fmaak_f32 v71, v146, v71, 0x3d2aaaab
	v_fmaak_f32 v71, v146, v71, 0x3e2aaaab
	v_fma_f32 v71, v146, v71, 0.5
	v_fma_f32 v71, v146, v71, 1.0
	v_mul_f32_e64 v71, v71, -v146
	v_fma_f32 v74, -v70, v70, 1.0
	v_cmp_lt_f32_e64 s[12:13], s84, v146
	v_add_f32_e32 v66, v66, v222
	v_add_f32_e32 v67, v67, v223
	v_cndmask_b32_e64 v71, v74, v71, s[12:13]
	v_sqrt_f32_e32 v74, v71
	v_mul_f32_e32 v71, 0x3fb8aa3b, v75
	v_fmamk_f32 v75, v147, 0x3ab60b61, v195
	v_mul_f32_e32 v64, 0xbfb8aa3b, v64
	v_mul_f32_e32 v65, 0xbfb8aa3b, v65
	v_mul_f32_e32 v66, 0xbfb8aa3b, v66
	v_mul_f32_e32 v67, 0xbfb8aa3b, v67
	v_exp_f32_e32 v71, v71
	v_fmaak_f32 v75, v147, v75, 0x3d2aaaab
	v_exp_f32_e32 v64, v64
	v_exp_f32_e32 v65, v65
	v_exp_f32_e32 v66, v66
	v_exp_f32_e32 v67, v67
	v_fmaak_f32 v75, v147, v75, 0x3e2aaaab
	v_fma_f32 v75, v147, v75, 0.5
	v_fma_f32 v75, v147, v75, 1.0
	v_cmp_lt_f32_e64 s[8:9], s84, v147
	v_mul_f32_e64 v75, v75, -v147
	v_fma_f32 v146, -v71, v71, 1.0
	v_add_f32_e32 v64, 1.0, v64
	v_add_f32_e32 v65, 1.0, v65
	v_add_f32_e32 v66, 1.0, v66
	v_add_f32_e32 v67, 1.0, v67
	v_cndmask_b32_e64 v75, v146, v75, s[8:9]
	v_rcp_f32_e32 v64, v64
	v_rcp_f32_e32 v65, v65
	v_sqrt_f32_e32 v73, v73
	v_rcp_f32_e32 v66, v66
	v_rcp_f32_e32 v67, v67
	v_sqrt_f32_e32 v75, v75
	v_pk_mul_f32 v[64:65], v[64:65], v[72:73]
	v_pk_mul_f32 v[66:67], v[66:67], v[74:75]
	v_pk_mul_f32 v[72:73], v[64:65], v[174:175]
	v_pk_mul_f32 v[74:75], v[66:67], v[172:173]
	v_add3_u32 v66, s60, v167, v144
	v_lshl_add_u64 v[64:65], v[142:143], 0, s[22:23]
	ds_write_b128 v66, v[68:71] offset:8192
	ds_write_b128 v66, v[72:75] offset:24576
	v_lshlrev_b64 v[64:65], 2, v[64:65]
	v_lshl_add_u64 v[68:69], s[2:3], 0, v[64:65]
	s_mov_b64 s[2:3], s[48:49]
	v_bitop3_b32 v67, v165, v163, 2 bitop3:0x36
	v_lshl_add_u64 v[72:73], s[2:3], 0, v[64:65]
	s_mov_b64 s[2:3], s[74:75]
	s_add_u32 s2, s2, s30
	s_addc_u32 s3, s3, 0
	v_lshl_add_u64 v[142:143], s[2:3], 0, v[144:145]
	v_add_co_u32_e64 v142, s[8:9], s37, v142
	v_lshlrev_b32_e32 v67, 4, v67
	s_nop 0
	v_addc_co_u32_e64 v143, s[8:9], 0, v143, s[8:9]
	v_add3_u32 v67, v166, v67, v164
	ds_read_b64 v[142:143], v67
	s_mov_b64 s[2:3], s[44:45]
	s_waitcnt lgkmcnt(0)
	v_lshlrev_b32_e32 v168, 16, v142
	v_and_b32_e32 v169, 0xffff0000, v142
	v_lshlrev_b32_e32 v142, 16, v143
	v_and_b32_e32 v143, 0xffff0000, v143
	v_add_f32_e32 v60, v60, v228
	v_mul_f32_e32 v60, 0xbfb8aa3b, v60
	v_exp_f32_e32 v60, v60
	v_add_f32_e32 v62, v62, v230
	v_add_f32_e32 v56, v56, v232
	v_mul_f32_e32 v56, 0xbfb8aa3b, v56
	v_exp_f32_e32 v56, v56
	v_add_f32_e32 v58, v58, v234
	v_mul_f32_e32 v58, 0xbfb8aa3b, v58
	v_exp_f32_e32 v58, v58
	v_add_f32_e32 v56, 1.0, v56
	v_rcp_f32_e32 v68, v56
	v_add_f32_e32 v56, v61, v229
	v_mul_f32_e32 v56, 0xbfb8aa3b, v56
	v_exp_f32_e32 v56, v56
	v_add_f32_e32 v60, 1.0, v60
	v_rcp_f32_e32 v60, v60
	v_add_f32_e32 v58, 1.0, v58
	v_add_f32_e32 v56, 1.0, v56
	v_rcp_f32_e32 v61, v56
	v_add_f32_e32 v56, v57, v233
	v_mul_f32_e32 v56, 0xbfb8aa3b, v56
	v_exp_f32_e32 v56, v56
	v_rcp_f32_e32 v70, v58
	v_add_f32_e32 v58, v63, v231
	v_mul_f32_e32 v58, 0xbfb8aa3b, v58
	v_add_f32_e32 v56, 1.0, v56
	v_rcp_f32_e32 v69, v56
	v_pk_mul_f32 v[56:57], v[60:61], s[38:39] op_sel_hi:[1,0]
	v_exp_f32_e32 v58, v58
	v_pk_mul_f32 v[60:61], v[236:237], v[56:57]
	v_mul_f32_e32 v62, 0xbfb8aa3b, v62
	v_pk_add_f32 v[72:73], v[60:61], v[60:61]
	v_mul_f32_e32 v56, 0x3fb8aa3b, v60
	v_fmamk_f32 v57, v72, 0x3ab60b61, v195
	v_exp_f32_e32 v56, v56
	v_fmaak_f32 v57, v72, v57, 0x3d2aaaab
	v_exp_f32_e32 v62, v62
	v_fmaak_f32 v57, v72, v57, 0x3e2aaaab
	v_add_f32_e32 v58, 1.0, v58
	v_fma_f32 v57, v72, v57, 0.5
	v_rcp_f32_e32 v63, v58
	v_add_f32_e32 v58, v59, v235
	v_fma_f32 v57, v72, v57, 1.0
	v_mul_f32_e32 v58, 0xbfb8aa3b, v58
	v_mul_f32_e64 v57, v57, -v72
	v_fma_f32 v60, -v56, v56, 1.0
	v_cmp_lt_f32_e64 s[12:13], s84, v72
	v_add_f32_e32 v62, 1.0, v62
	v_exp_f32_e32 v58, v58
	v_cndmask_b32_e64 v57, v60, v57, s[12:13]
	v_rcp_f32_e32 v62, v62
	v_sqrt_f32_e32 v60, v57
	v_mul_f32_e32 v57, 0x3fb8aa3b, v61
	v_fmamk_f32 v61, v73, 0x3ab60b61, v195
	v_fmaak_f32 v61, v73, v61, 0x3d2aaaab
	v_fmaak_f32 v61, v73, v61, 0x3e2aaaab
	v_add_f32_e32 v58, 1.0, v58
	v_fma_f32 v61, v73, v61, 0.5
	v_rcp_f32_e32 v71, v58
	v_pk_mul_f32 v[58:59], v[62:63], s[38:39] op_sel_hi:[1,0]
	v_fma_f32 v61, v73, v61, 1.0
	v_pk_mul_f32 v[62:63], v[238:239], v[58:59]
	v_cmp_lt_f32_e64 s[8:9], s84, v73
	v_mul_f32_e64 v61, v61, -v73
	v_pk_add_f32 v[72:73], v[62:63], v[62:63]
	v_mul_f32_e32 v58, 0x3fb8aa3b, v62
	v_fmamk_f32 v59, v72, 0x3ab60b61, v195
	v_exp_f32_e32 v58, v58
	v_fmaak_f32 v59, v72, v59, 0x3d2aaaab
	v_fmaak_f32 v59, v72, v59, 0x3e2aaaab
	v_fma_f32 v59, v72, v59, 0.5
	v_fma_f32 v59, v72, v59, 1.0
	v_mul_f32_e64 v59, v59, -v72
	v_fma_f32 v62, -v58, v58, 1.0
	v_cmp_lt_f32_e64 s[12:13], s84, v72
	v_exp_f32_e32 v57, v57
	s_nop 0
	v_cndmask_b32_e64 v59, v62, v59, s[12:13]
	v_sqrt_f32_e32 v62, v59
	v_mul_f32_e32 v59, 0x3fb8aa3b, v63
	v_fmamk_f32 v63, v73, 0x3ab60b61, v195
	v_exp_f32_e32 v59, v59
	v_fmaak_f32 v63, v73, v63, 0x3d2aaaab
	v_fmaak_f32 v63, v73, v63, 0x3e2aaaab
	v_fma_f32 v63, v73, v63, 0.5
	v_fma_f32 v67, -v57, v57, 1.0
	v_fma_f32 v63, v73, v63, 1.0
	v_cndmask_b32_e64 v61, v67, v61, s[8:9]
	v_cmp_lt_f32_e64 s[8:9], s84, v73
	v_mul_f32_e64 v63, v63, -v73
	v_fma_f32 v67, -v59, v59, 1.0
	v_cndmask_b32_e64 v63, v67, v63, s[8:9]
	v_sqrt_f32_e32 v61, v61
	v_sqrt_f32_e32 v63, v63
	v_bitop3_b32 v67, v165, v163, 4 bitop3:0x36
	v_lshlrev_b32_e32 v67, 4, v67
	v_pk_mul_f32 v[60:61], v[68:69], v[60:61]
	v_pk_mul_f32 v[62:63], v[70:71], v[62:63]
	v_pk_mul_f32 v[60:61], v[60:61], v[168:169]
	v_pk_mul_f32 v[62:63], v[62:63], v[142:143]
	ds_write_b128 v66, v[56:59] offset:8256
	ds_write_b128 v66, v[60:63] offset:24640
	v_add3_u32 v67, v166, v67, v164
	v_lshl_add_u64 v[56:57], s[2:3], 0, v[64:65]
	s_mov_b64 s[2:3], s[48:49]
	s_waitcnt vmcnt(0) lgkmcnt(0)
	v_add_f32_e32 v52, v52, v240
	v_lshl_add_u64 v[60:61], s[2:3], 0, v[64:65]
	s_mov_b64 s[2:3], s[74:75]
	s_add_u32 s2, s2, s30
	s_addc_u32 s3, s3, 0
	v_lshl_add_u64 v[68:69], s[2:3], 0, v[144:145]
	v_add_co_u32_e64 v68, s[8:9], s37, v68
	v_mul_f32_e32 v52, 0xbfb8aa3b, v52
	s_nop 0
	v_addc_co_u32_e64 v69, s[8:9], 0, v69, s[8:9]
	v_exp_f32_e32 v52, v52
	v_add_f32_e32 v54, v54, v242
	v_mul_f32_e32 v54, 0xbfb8aa3b, v54
	v_exp_f32_e32 v54, v54
	v_add_f32_e32 v52, 1.0, v52
	v_rcp_f32_e32 v52, v52
	ds_read_b64 v[72:73], v67
	v_add_f32_e32 v54, 1.0, v54
	v_rcp_f32_e32 v54, v54
	s_mov_b64 s[2:3], s[44:45]
	s_waitcnt lgkmcnt(0)
	v_lshlrev_b32_e32 v74, 16, v72
	v_and_b32_e32 v75, 0xffff0000, v72
	v_lshlrev_b32_e32 v72, 16, v73
	v_and_b32_e32 v73, 0xffff0000, v73
	v_add_f32_e32 v48, v48, v244
	v_mul_f32_e32 v48, 0xbfb8aa3b, v48
	v_exp_f32_e32 v48, v48
	v_add_f32_e32 v50, v50, v246
	v_mul_f32_e32 v50, 0xbfb8aa3b, v50
	v_exp_f32_e32 v50, v50
	v_add_f32_e32 v48, 1.0, v48
	v_rcp_f32_e32 v56, v48
	v_add_f32_e32 v48, v53, v241
	v_mul_f32_e32 v48, 0xbfb8aa3b, v48
	v_exp_f32_e32 v48, v48
	v_add_f32_e32 v50, 1.0, v50
	v_rcp_f32_e32 v58, v50
	v_add_f32_e32 v50, v55, v243
	v_add_f32_e32 v48, 1.0, v48
	v_rcp_f32_e32 v53, v48
	v_add_f32_e32 v48, v49, v245
	v_mul_f32_e32 v48, 0xbfb8aa3b, v48
	v_exp_f32_e32 v48, v48
	v_mul_f32_e32 v50, 0xbfb8aa3b, v50
	v_exp_f32_e32 v50, v50
	v_add_f32_e32 v48, 1.0, v48
	v_rcp_f32_e32 v57, v48
	v_pk_mul_f32 v[48:49], v[52:53], s[38:39] op_sel_hi:[1,0]
	v_add_f32_e32 v50, 1.0, v50
	v_pk_mul_f32 v[52:53], v[248:249], v[48:49]
	v_rcp_f32_e32 v55, v50
	v_pk_add_f32 v[60:61], v[52:53], v[52:53]
	v_mul_f32_e32 v48, 0x3fb8aa3b, v52
	v_fmamk_f32 v49, v60, 0x3ab60b61, v195
	v_exp_f32_e32 v48, v48
	v_fmaak_f32 v49, v60, v49, 0x3d2aaaab
	v_fmaak_f32 v49, v60, v49, 0x3e2aaaab
	v_fma_f32 v49, v60, v49, 0.5
	v_fma_f32 v49, v60, v49, 1.0
	v_add_f32_e32 v50, v51, v247
	v_mul_f32_e64 v49, v49, -v60
	v_fma_f32 v52, -v48, v48, 1.0
	v_cmp_lt_f32_e64 s[12:13], s84, v60
	v_mul_f32_e32 v50, 0xbfb8aa3b, v50
	v_exp_f32_e32 v50, v50
	v_cndmask_b32_e64 v49, v52, v49, s[12:13]
	v_sqrt_f32_e32 v52, v49
	v_mul_f32_e32 v49, 0x3fb8aa3b, v53
	v_fmamk_f32 v53, v61, 0x3ab60b61, v195
	v_exp_f32_e32 v49, v49
	v_fmaak_f32 v53, v61, v53, 0x3d2aaaab
	v_fmaak_f32 v53, v61, v53, 0x3e2aaaab
	v_fma_f32 v53, v61, v53, 0.5
	v_add_f32_e32 v50, 1.0, v50
	v_fma_f32 v53, v61, v53, 1.0
	v_rcp_f32_e32 v59, v50
	v_pk_mul_f32 v[50:51], v[54:55], s[38:39] op_sel_hi:[1,0]
	v_cmp_lt_f32_e64 s[8:9], s84, v61
	v_mul_f32_e64 v53, v53, -v61
	v_fma_f32 v60, -v49, v49, 1.0
	v_pk_mul_f32 v[54:55], v[250:251], v[50:51]
	v_cndmask_b32_e64 v53, v60, v53, s[8:9]
	v_pk_add_f32 v[60:61], v[54:55], v[54:55]
	v_mul_f32_e32 v50, 0x3fb8aa3b, v54
	v_fmamk_f32 v51, v60, 0x3ab60b61, v195
	v_exp_f32_e32 v50, v50
	v_fmaak_f32 v51, v60, v51, 0x3d2aaaab
	v_fmaak_f32 v51, v60, v51, 0x3e2aaaab
	v_fma_f32 v51, v60, v51, 0.5
	v_fma_f32 v51, v60, v51, 1.0
	v_mul_f32_e64 v51, v51, -v60
	v_fma_f32 v54, -v50, v50, 1.0
	v_cmp_lt_f32_e64 s[12:13], s84, v60
	v_cmp_lt_f32_e64 s[8:9], s84, v61
	v_sqrt_f32_e32 v53, v53
	v_cndmask_b32_e64 v51, v54, v51, s[12:13]
	v_sqrt_f32_e32 v54, v51
	v_mul_f32_e32 v51, 0x3fb8aa3b, v55
	v_fmamk_f32 v55, v61, 0x3ab60b61, v195
	v_exp_f32_e32 v51, v51
	v_fmaak_f32 v55, v61, v55, 0x3d2aaaab
	v_fmaak_f32 v55, v61, v55, 0x3e2aaaab
	v_fma_f32 v55, v61, v55, 0.5
	v_fma_f32 v55, v61, v55, 1.0
	v_mul_f32_e64 v55, v55, -v61
	v_fma_f32 v60, -v51, v51, 1.0
	v_cndmask_b32_e64 v55, v60, v55, s[8:9]
	v_sqrt_f32_e32 v55, v55
	v_pk_mul_f32 v[52:53], v[56:57], v[52:53]
	v_bitop3_b32 v60, v165, v163, 6 bitop3:0x36
	v_pk_mul_f32 v[52:53], v[52:53], v[74:75]
	v_pk_mul_f32 v[54:55], v[58:59], v[54:55]
	v_lshlrev_b32_e32 v60, 4, v60
	v_pk_mul_f32 v[54:55], v[54:55], v[72:73]
	ds_write_b128 v66, v[48:51] offset:8320
	ds_write_b128 v66, v[52:55] offset:24704
	v_add3_u32 v60, v166, v60, v164
	v_lshl_add_u64 v[48:49], s[2:3], 0, v[64:65]
	s_mov_b64 s[2:3], s[48:49]
	s_waitcnt vmcnt(0) lgkmcnt(0)
	v_add_f32_e32 v12, v12, v178
	v_lshl_add_u64 v[52:53], s[2:3], 0, v[64:65]
	s_mov_b64 s[2:3], s[74:75]
	s_add_u32 s2, s2, s30
	s_addc_u32 s3, s3, 0
	v_lshl_add_u64 v[56:57], s[2:3], 0, v[144:145]
	v_add_co_u32_e64 v56, s[8:9], s37, v56
	v_mul_f32_e32 v12, 0xbfb8aa3b, v12
	s_nop 0
	v_addc_co_u32_e64 v57, s[8:9], 0, v57, s[8:9]
	flat_load_dwordx4 v[56:59], v[56:57] offset:192
	v_exp_f32_e32 v12, v12
	v_add_f32_e32 v14, v14, v180
	v_mul_f32_e32 v14, 0xbfb8aa3b, v14
	v_exp_f32_e32 v14, v14
	v_add_f32_e32 v12, 1.0, v12
	v_rcp_f32_e32 v12, v12
	ds_read_b64 v[60:61], v60
	v_add_f32_e32 v14, 1.0, v14
	v_rcp_f32_e32 v14, v14
	s_waitcnt lgkmcnt(0)
	v_lshlrev_b32_e32 v62, 16, v60
	v_and_b32_e32 v63, 0xffff0000, v60
	v_lshlrev_b32_e32 v60, 16, v61
	v_and_b32_e32 v61, 0xffff0000, v61
	s_waitcnt vmcnt(0)
	v_add_f32_e32 v8, v8, v182
	v_mul_f32_e32 v8, 0xbfb8aa3b, v8
	v_exp_f32_e32 v8, v8
	v_add_f32_e32 v10, v10, v184
	v_mul_f32_e32 v10, 0xbfb8aa3b, v10
	v_exp_f32_e32 v10, v10
	v_add_f32_e32 v8, 1.0, v8
	v_rcp_f32_e32 v48, v8
	v_add_f32_e32 v8, v13, v179
	v_mul_f32_e32 v8, 0xbfb8aa3b, v8
	v_exp_f32_e32 v8, v8
	v_add_f32_e32 v10, 1.0, v10
	v_rcp_f32_e32 v50, v10
	v_add_f32_e32 v10, v15, v181
	v_add_f32_e32 v8, 1.0, v8
	v_rcp_f32_e32 v13, v8
	v_add_f32_e32 v8, v9, v183
	v_mul_f32_e32 v8, 0xbfb8aa3b, v8
	v_exp_f32_e32 v8, v8
	v_mul_f32_e32 v10, 0xbfb8aa3b, v10
	v_exp_f32_e32 v10, v10
	v_add_f32_e32 v8, 1.0, v8
	v_rcp_f32_e32 v49, v8
	v_pk_mul_f32 v[8:9], v[12:13], s[38:39] op_sel_hi:[1,0]
	v_add_f32_e32 v10, 1.0, v10
	v_pk_mul_f32 v[12:13], v[56:57], v[8:9]
	v_rcp_f32_e32 v15, v10
	v_pk_add_f32 v[52:53], v[12:13], v[12:13]
	v_mul_f32_e32 v8, 0x3fb8aa3b, v12
	v_fmamk_f32 v9, v52, 0x3ab60b61, v195
	v_exp_f32_e32 v8, v8
	v_fmaak_f32 v9, v52, v9, 0x3d2aaaab
	v_fmaak_f32 v9, v52, v9, 0x3e2aaaab
	v_fma_f32 v9, v52, v9, 0.5
	v_fma_f32 v9, v52, v9, 1.0
	v_add_f32_e32 v10, v11, v185
	v_mul_f32_e64 v9, v9, -v52
	v_fma_f32 v12, -v8, v8, 1.0
	v_cmp_lt_f32_e64 s[12:13], s84, v52
	v_mul_f32_e32 v10, 0xbfb8aa3b, v10
	v_exp_f32_e32 v10, v10
	v_cndmask_b32_e64 v9, v12, v9, s[12:13]
	v_sqrt_f32_e32 v12, v9
	v_mul_f32_e32 v9, 0x3fb8aa3b, v13
	v_fmamk_f32 v13, v53, 0x3ab60b61, v195
	v_exp_f32_e32 v9, v9
	v_fmaak_f32 v13, v53, v13, 0x3d2aaaab
	v_fmaak_f32 v13, v53, v13, 0x3e2aaaab
	v_fma_f32 v13, v53, v13, 0.5
	v_add_f32_e32 v10, 1.0, v10
	v_fma_f32 v13, v53, v13, 1.0
	v_rcp_f32_e32 v51, v10
	v_pk_mul_f32 v[10:11], v[14:15], s[38:39] op_sel_hi:[1,0]
	v_cmp_lt_f32_e64 s[8:9], s84, v53
	v_mul_f32_e64 v13, v13, -v53
	v_fma_f32 v52, -v9, v9, 1.0
	v_pk_mul_f32 v[14:15], v[58:59], v[10:11]
	v_cndmask_b32_e64 v13, v52, v13, s[8:9]
	v_pk_add_f32 v[52:53], v[14:15], v[14:15]
	v_mul_f32_e32 v10, 0x3fb8aa3b, v14
	v_fmamk_f32 v11, v52, 0x3ab60b61, v195
	v_exp_f32_e32 v10, v10
	v_fmaak_f32 v11, v52, v11, 0x3d2aaaab
	v_fmaak_f32 v11, v52, v11, 0x3e2aaaab
	v_fma_f32 v11, v52, v11, 0.5
	v_fma_f32 v11, v52, v11, 1.0
	v_mul_f32_e64 v11, v11, -v52
	v_fma_f32 v14, -v10, v10, 1.0
	v_cmp_lt_f32_e64 s[12:13], s84, v52
	v_cmp_lt_f32_e64 s[8:9], s84, v53
	v_sqrt_f32_e32 v13, v13
	v_cndmask_b32_e64 v11, v14, v11, s[12:13]
	v_sqrt_f32_e32 v14, v11
	v_mul_f32_e32 v11, 0x3fb8aa3b, v15
	v_fmamk_f32 v15, v53, 0x3ab60b61, v195
	v_exp_f32_e32 v11, v11
	v_fmaak_f32 v15, v53, v15, 0x3d2aaaab
	v_fmaak_f32 v15, v53, v15, 0x3e2aaaab
	v_fma_f32 v15, v53, v15, 0.5
	v_fma_f32 v15, v53, v15, 1.0
	v_mul_f32_e64 v15, v15, -v53
	v_fma_f32 v52, -v11, v11, 1.0
	v_cndmask_b32_e64 v15, v52, v15, s[8:9]
	v_sqrt_f32_e32 v15, v15
	v_pk_mul_f32 v[12:13], v[48:49], v[12:13]
	v_cmp_lt_i32_e64 s[8:9], 0, v141
	v_pk_mul_f32 v[12:13], v[12:13], v[62:63]
	v_pk_mul_f32 v[14:15], v[50:51], v[14:15]
	s_nop 0
	v_pk_mul_f32 v[14:15], v[14:15], v[60:61]
	ds_write_b128 v66, v[8:11] offset:8384
	ds_write_b128 v66, v[12:15] offset:24768
	v_and_b32_e32 v9, 63, v162
	v_lshlrev_b32_e32 v64, 2, v9
	v_lshl_or_b32 v8, v141, 12, v64
	v_add_u32_e32 v8, s60, v8
	s_waitcnt lgkmcnt(0)
	s_barrier
	ds_read2st64_b32 v[10:11], v8 offset0:32 offset1:33
	ds_read2st64_b32 v[12:13], v8 offset0:96 offset1:97
	ds_read2st64_b32 v[14:15], v8 offset0:34 offset1:35
	ds_read2st64_b32 v[48:49], v8 offset0:98 offset1:99
	v_lshl_add_u32 v9, v9, 3, s60
	s_waitcnt lgkmcnt(2)
	v_fma_f32 v12, 0, v10, v12
	v_fmac_f32_e32 v13, v12, v11
	v_mul_f32_e32 v10, v10, v11
	s_waitcnt lgkmcnt(0)
	v_fma_f32 v11, v13, v14, v48
	ds_read2st64_b32 v[12:13], v8 offset0:36 offset1:37
	ds_read2st64_b32 v[50:51], v8 offset0:100 offset1:101
	v_fmac_f32_e32 v49, v11, v15
	v_mov_b32_e32 v58, v14
	v_mul_f32_e32 v14, v10, v14
	v_mul_f32_e32 v14, v14, v15
	s_waitcnt lgkmcnt(0)
	v_fma_f32 v11, v49, v12, v50
	ds_read2st64_b32 v[48:49], v8 offset0:38 offset1:39
	ds_read2st64_b32 v[52:53], v8 offset0:102 offset1:103
	v_fmac_f32_e32 v51, v11, v13
	s_waitcnt lgkmcnt(1)
	v_mov_b32_e32 v62, v48
	s_waitcnt lgkmcnt(0)
	v_fma_f32 v11, v51, v48, v52
	ds_read2st64_b32 v[50:51], v8 offset0:40 offset1:41
	ds_read2st64_b32 v[54:55], v8 offset0:104 offset1:105
	v_fmac_f32_e32 v53, v11, v49
	s_waitcnt lgkmcnt(1)
	v_mov_b32_e32 v59, v51
	s_waitcnt lgkmcnt(0)
	v_fmac_f32_e32 v54, v53, v50
	ds_read2st64_b32 v[52:53], v8 offset0:42 offset1:43
	ds_read2st64_b32 v[56:57], v8 offset0:106 offset1:107
	v_mov_b32_e32 v11, v54
	v_mov_b32_e32 v54, v15
	v_pk_fma_f32 v[10:11], v[10:11], v[58:59], v[54:55]
	v_mov_b32_e32 v58, v13
	v_mov_b32_e32 v15, v11
	v_mov_b32_e32 v10, v12
	s_waitcnt lgkmcnt(1)
	v_mov_b32_e32 v11, v52
	v_pk_mul_f32 v[54:55], v[14:15], v[10:11]
	v_mov_b32_e32 v12, v13
	s_waitcnt lgkmcnt(0)
	v_mov_b32_e32 v59, v56
	v_pk_mul_f32 v[12:13], v[54:55], v[12:13]
	v_pk_fma_f32 v[10:11], v[14:15], v[10:11], v[58:59]
	v_and_b32_e32 v56, 0x1fffffc0, v161
	v_mov_b32_e32 v10, v12
	ds_read2st64_b32 v[14:15], v8 offset0:44 offset1:45
	ds_read2st64_b32 v[54:55], v8 offset0:108 offset1:109
	ds_read2st64_b32 v[58:59], v8 offset0:46 offset1:47
	ds_read2st64_b32 v[60:61], v8 offset0:110 offset1:111
	v_lshl_add_u32 v65, v56, 3, v9
	v_mov_b32_e32 v63, v53
	v_pk_mul_f32 v[12:13], v[12:13], v[48:49]
	v_mov_b32_e32 v48, v49
	v_mov_b32_e32 v56, v49
	v_pk_mul_f32 v[12:13], v[12:13], v[48:49]
	v_pk_fma_f32 v[10:11], v[10:11], v[62:63], v[56:57]
	v_mov_b32_e32 v56, v51
	v_mov_b32_e32 v13, v11
	v_mov_b32_e32 v10, v50
	s_waitcnt lgkmcnt(3)
	v_mov_b32_e32 v11, v14
	v_pk_mul_f32 v[48:49], v[12:13], v[10:11]
	v_mov_b32_e32 v50, v51
	s_waitcnt lgkmcnt(2)
	v_mov_b32_e32 v57, v54
	v_pk_mul_f32 v[48:49], v[48:49], v[50:51]
	v_pk_fma_f32 v[10:11], v[12:13], v[10:11], v[56:57]
	v_mov_b32_e32 v12, v52
	v_mov_b32_e32 v10, v48
	v_mov_b32_e32 v13, v15
	v_pk_mul_f32 v[48:49], v[48:49], v[52:53]
	v_mov_b32_e32 v50, v53
	v_mov_b32_e32 v54, v53
	v_pk_mul_f32 v[48:49], v[48:49], v[50:51]
	v_pk_fma_f32 v[10:11], v[10:11], v[12:13], v[54:55]
	v_mov_b32_e32 v50, v15
	v_mov_b32_e32 v49, v11
	v_mov_b32_e32 v10, v14
	s_waitcnt lgkmcnt(1)
	v_mov_b32_e32 v11, v58
	v_pk_mul_f32 v[12:13], v[48:49], v[10:11]
	v_mov_b32_e32 v14, v15
	s_waitcnt lgkmcnt(0)
	v_mov_b32_e32 v51, v60
	v_pk_mul_f32 v[12:13], v[12:13], v[14:15]
	v_pk_fma_f32 v[10:11], v[48:49], v[10:11], v[50:51]
	v_mov_b32_e32 v14, v59
	v_mov_b32_e32 v10, v12
	v_pk_mul_f32 v[12:13], v[12:13], v[58:59]
	v_mov_b32_e32 v60, v59
	v_pk_mul_f32 v[12:13], v[12:13], v[14:15]
	v_pk_fma_f32 v[10:11], v[10:11], v[58:59], v[60:61]
	s_nop 0
	v_mov_b32_e32 v13, v11
	v_sub_u32_e32 v10, v9, v64
	ds_write_b64 v65, v[12:13] offset:40960
	s_waitcnt lgkmcnt(0)
	s_barrier
	ds_read_b32 v10, v10 offset:43008
	s_and_saveexec_b64 s[2:3], s[8:9]
	s_cbranch_execz .LBB0_359
	ds_read_b64 v[12:13], v9 offset:40960
	s_waitcnt lgkmcnt(0)
	v_fmac_f32_e32 v13, v10, v12
	v_mov_b32_e32 v10, v13
	s_or_b64 exec, exec, s[2:3]
	v_cmp_lt_i32_e64 s[8:9], 1, v141
	s_and_saveexec_b64 s[2:3], s[8:9]
	s_cbranch_execnz .LBB0_360

.LBB0_363:
	s_or_b64 exec, exec, s[2:3]
	s_mov_b64 s[2:3], s[74:75]
	ds_read2st64_b32 v[12:13], v8 offset0:32 offset1:33
	ds_read2st64_b32 v[14:15], v8 offset0:96 offset1:97
	v_mov_b32_e32 v162, v191
	v_mov_b32_e32 v163, v191
	s_mov_b64 s[2:3], s[74:75]
	v_mov_b32_e32 v143, v145
	s_waitcnt lgkmcnt(0)
	v_fma_f32 v9, v10, v12, v14
	v_fmac_f32_e32 v15, v9, v13
	ds_write2st64_b32 v8, v9, v15 offset0:176 offset1:177
	ds_read2st64_b32 v[10:11], v8 offset0:34 offset1:35
	ds_read2st64_b32 v[12:13], v8 offset0:98 offset1:99
	v_readlane_b32 s40, v254, 22
	v_readlane_b32 s44, v254, 26
	v_readlane_b32 s45, v254, 27
	v_readlane_b32 s48, v254, 30
	s_waitcnt lgkmcnt(0)
	v_fma_f32 v9, v15, v10, v12
	v_fmac_f32_e32 v13, v9, v11
	ds_write2st64_b32 v8, v9, v13 offset0:178 offset1:179
	ds_read2st64_b32 v[10:11], v8 offset0:36 offset1:37
	ds_read2st64_b32 v[14:15], v8 offset0:100 offset1:101
	v_readlane_b32 s49, v254, 31
	s_mov_b64 s[8:9], s[48:49]
	v_readlane_b32 s41, v254, 23
	v_readlane_b32 s42, v254, 24
	s_waitcnt lgkmcnt(0)
	v_fma_f32 v9, v13, v10, v14
	v_fmac_f32_e32 v15, v9, v11
	ds_write2st64_b32 v8, v9, v15 offset0:180 offset1:181
	ds_read2st64_b32 v[10:11], v8 offset0:38 offset1:39
	ds_read2st64_b32 v[12:13], v8 offset0:102 offset1:103
	v_readlane_b32 s43, v254, 25
	v_readlane_b32 s46, v254, 28
	v_readlane_b32 s47, v254, 29
	v_readlane_b32 s50, v254, 32
	s_waitcnt lgkmcnt(0)
	v_fma_f32 v9, v15, v10, v12
	v_fmac_f32_e32 v13, v9, v11
	ds_write2st64_b32 v8, v9, v13 offset0:182 offset1:183
	ds_read2st64_b32 v[10:11], v8 offset0:40 offset1:41
	ds_read2st64_b32 v[14:15], v8 offset0:104 offset1:105
	v_readlane_b32 s51, v254, 33
	v_readlane_b32 s52, v254, 34
	v_readlane_b32 s53, v254, 35
	v_readlane_b32 s54, v254, 36
	s_waitcnt lgkmcnt(0)
	v_fma_f32 v9, v13, v10, v14
	v_fmac_f32_e32 v15, v9, v11
	ds_write2st64_b32 v8, v9, v15 offset0:184 offset1:185
	ds_read2st64_b32 v[10:11], v8 offset0:42 offset1:43
	ds_read2st64_b32 v[12:13], v8 offset0:106 offset1:107
	v_readlane_b32 s55, v254, 37
	s_waitcnt lgkmcnt(0)
	v_fma_f32 v9, v15, v10, v12
	v_fmac_f32_e32 v13, v9, v11
	ds_write2st64_b32 v8, v9, v13 offset0:186 offset1:187
	ds_read2st64_b32 v[10:11], v8 offset0:44 offset1:45
	ds_read2st64_b32 v[14:15], v8 offset0:108 offset1:109
	s_waitcnt lgkmcnt(0)
	v_fma_f32 v9, v13, v10, v14
	v_fmac_f32_e32 v15, v9, v11
	ds_write2st64_b32 v8, v9, v15 offset0:188 offset1:189
	ds_read2st64_b32 v[10:11], v8 offset0:46 offset1:47
	ds_read2st64_b32 v[12:13], v8 offset0:110 offset1:111
	s_waitcnt lgkmcnt(0)
	v_fma_f32 v9, v15, v10, v12
	v_fmac_f32_e32 v13, v9, v11
	ds_write2st64_b32 v8, v9, v13 offset0:190 offset1:191
	s_waitcnt lgkmcnt(0)
	s_barrier
	s_add_u32 s2, s2, s31
	v_and_b32_e32 v165, 15, v162
	v_lshrrev_b32_e32 v170, 4, v162
	v_bfe_u32 v171, v162, 4, 2
	v_bfe_u32 v164, v162, 1, 3
	v_ashrrev_i32_e32 v161, 6, v162
	v_lshlrev_b32_e32 v142, 7, v165
	v_bitop3_b32 v8, v170, v164, 3 bitop3:0x6c
	v_bitop3_b32 v13, v171, v164, 4 bitop3:0x36
	v_lshl_or_b32 v12, v161, 11, v142
	v_lshlrev_b32_e32 v8, 4, v8
	v_lshlrev_b32_e32 v13, 4, v13
	v_add3_u32 v8, s60, v8, v12
	v_add3_u32 v12, s60, v13, v12
	s_addc_u32 s3, s3, 0
	v_lshlrev_b32_e32 v144, 4, v171
	ds_read_b128 v[8:11], v8
	ds_read_b128 v[72:75], v12
	v_lshl_add_u64 v[12:13], s[2:3], 0, v[144:145]
	s_mov_b64 s[2:3], 0x3980000
	v_lshl_add_u64 v[166:167], v[12:13], 0, s[2:3]
	s_mov_b64 s[2:3], 0x39a0000
	v_lshl_add_u64 v[168:169], v[12:13], 0, s[2:3]
	v_lshl_add_u64 v[60:61], v[166:167], 0, v[142:143]
	v_lshl_add_u64 v[62:63], v[168:169], 0, v[142:143]
	flat_load_dwordx4 v[12:15], v[60:61]
	flat_load_dwordx4 v[48:51], v[62:63]
	flat_load_dwordx4 v[52:55], v[60:61] offset:64
	flat_load_dwordx4 v[56:59], v[62:63] offset:64
	v_lshrrev_b32_e32 v172, 1, v162
	v_lshlrev_b32_e32 v141, 4, v161
	s_mov_b64 s[2:3], s[44:45]
	s_waitcnt vmcnt(0) lgkmcnt(0)
	v_mfma_f32_16x16x32_bf16 v[12:15], v[12:15], v[8:11], 0
	v_mfma_f32_16x16x32_bf16 v[48:51], v[48:51], v[8:11], 0
	v_mfma_f32_16x16x32_bf16 v[68:71], v[52:55], v[72:75], v[12:15]
	v_mfma_f32_16x16x32_bf16 v[64:67], v[56:59], v[72:75], v[48:51]
	s_nop 4
	flat_load_dwordx4 v[12:15], v[60:61] offset:2048
	flat_load_dwordx4 v[48:51], v[62:63] offset:2048
	flat_load_dwordx4 v[52:55], v[60:61] offset:2112
	flat_load_dwordx4 v[56:59], v[62:63] offset:2112
	s_waitcnt vmcnt(0) lgkmcnt(0)
	v_mfma_f32_16x16x32_bf16 v[12:15], v[12:15], v[8:11], 0
	v_mfma_f32_16x16x32_bf16 v[48:51], v[48:51], v[8:11], 0
	v_mfma_f32_16x16x32_bf16 v[60:63], v[52:55], v[72:75], v[12:15]
	s_nop 5
	v_or_b32_e32 v12, 0x1000, v142
	v_mov_b32_e32 v13, v145
	v_lshl_add_u64 v[52:53], v[166:167], 0, v[12:13]
	v_mfma_f32_16x16x32_bf16 v[56:59], v[56:59], v[72:75], v[48:51]
	v_lshl_add_u64 v[146:147], v[168:169], 0, v[12:13]
	flat_load_dwordx4 v[12:15], v[52:53]
	s_nop 0
	flat_load_dwordx4 v[48:51], v[146:147]
	s_nop 0
	flat_load_dwordx4 v[52:55], v[52:53] offset:64
	s_nop 0
	flat_load_dwordx4 v[146:149], v[146:147] offset:64
	s_waitcnt vmcnt(0) lgkmcnt(0)
	v_mfma_f32_16x16x32_bf16 v[12:15], v[12:15], v[8:11], 0
	v_mfma_f32_16x16x32_bf16 v[48:51], v[48:51], v[8:11], 0
	v_mfma_f32_16x16x32_bf16 v[52:55], v[52:55], v[72:75], v[12:15]
	s_nop 5
	v_or_b32_e32 v12, 0x1800, v142
	v_mov_b32_e32 v13, v145
	v_lshl_add_u64 v[142:143], v[166:167], 0, v[12:13]
	v_mfma_f32_16x16x32_bf16 v[48:51], v[146:149], v[72:75], v[48:51]
	v_lshl_add_u64 v[166:167], v[168:169], 0, v[12:13]
	flat_load_dwordx4 v[12:15], v[142:143]
	flat_load_dwordx4 v[146:149], v[166:167]
	s_waitcnt vmcnt(0) lgkmcnt(0)
	v_mfma_f32_16x16x32_bf16 v[12:15], v[12:15], v[8:11], 0
	v_mfma_f32_16x16x32_bf16 v[8:11], v[146:149], v[8:11], 0
	flat_load_dwordx4 v[146:149], v[142:143] offset:64
	s_nop 0
	flat_load_dwordx4 v[166:169], v[166:167] offset:64
	v_lshlrev_b32_e32 v142, 2, v171
	v_mov_b32_e32 v143, v145
	v_or_b32_e32 v180, s22, v142
	v_ashrrev_i32_e32 v181, 31, v180
	v_lshlrev_b64 v[180:181], 2, v[180:181]
	s_add_u32 s98, s74, s30
	s_addc_u32 s99, s75, 0
	s_add_u32 s98, s98, 0x122e6000
	s_addc_u32 s99, s99, 0
	v_lshl_add_u64 v[184:185], s[98:99], 0, v[144:145]
	v_lshl_add_u64 v[178:179], s[44:45], 0, v[180:181]
	v_lshl_add_u64 v[182:183], s[48:49], 0, v[180:181]
	global_load_dwordx4 v[216:219], v[178:179], off offset:2048
	global_load_dwordx4 v[220:223], v[182:183], off offset:2048
	global_load_dwordx4 v[224:227], v[184:185], off offset:2048
	global_load_dwordx4 v[228:231], v[178:179], off offset:2112
	global_load_dwordx4 v[232:235], v[182:183], off offset:2112
	global_load_dwordx4 v[236:239], v[184:185], off offset:2112
	global_load_dwordx4 v[240:243], v[178:179], off offset:2176
	global_load_dwordx4 v[244:247], v[182:183], off offset:2176
	global_load_dwordx4 v[248:251], v[184:185], off offset:2176
	global_load_dwordx4 v[178:181], v[178:179], off offset:2240
	global_load_dwordx4 v[182:185], v[182:183], off offset:2240
	s_waitcnt vmcnt(0) lgkmcnt(0)
	v_mfma_f32_16x16x32_bf16 v[12:15], v[146:149], v[72:75], v[12:15]
	v_mfma_f32_16x16x32_bf16 v[8:11], v[166:169], v[72:75], v[8:11]
	v_or_b32_e32 v72, v141, v165
	v_and_b32_e32 v73, 8, v172
	v_lshlrev_b32_e32 v165, 7, v72
	v_add_u32_e32 v167, s60, v73
	v_lshlrev_b32_e32 v176, 8, v72
	v_lshl_add_u64 v[72:73], v[142:143], 0, s[22:23]
	v_lshlrev_b64 v[146:147], 2, v[72:73]
	v_lshl_add_u64 v[72:73], s[2:3], 0, v[146:147]
	s_mov_b64 s[2:3], s[74:75]
	v_lshl_add_u64 v[146:147], s[8:9], 0, v[146:147]
	s_add_u32 s2, s2, s30
	s_addc_u32 s3, s3, 0
	v_lshl_add_u64 v[168:169], s[2:3], 0, v[144:145]
	v_add_co_u32_e64 v168, s[8:9], s37, v168
	v_bfe_u32 v166, v170, 1, 1
	s_nop 0
	v_addc_co_u32_e64 v169, s[8:9], 0, v169, s[8:9]
	v_bitop3_b32 v172, v166, v172, 7 bitop3:0x78
	v_lshlrev_b32_e32 v172, 4, v172
	v_add3_u32 v172, v167, v172, v165
	ds_read_b64 v[172:173], v172
	s_mov_b64 s[2:3], s[44:45]
	s_waitcnt lgkmcnt(0)
	v_lshlrev_b32_e32 v174, 16, v172
	v_and_b32_e32 v175, 0xffff0000, v172
	v_lshlrev_b32_e32 v172, 16, v173
	v_and_b32_e32 v173, 0xffff0000, v173
	v_add_f32_e32 v68, v68, v216
	v_add_f32_e32 v69, v69, v217
	v_mul_f32_e32 v68, 0xbfb8aa3b, v68
	v_mul_f32_e32 v69, 0xbfb8aa3b, v69
	v_exp_f32_e32 v68, v68
	v_exp_f32_e32 v69, v69
	v_add_f32_e32 v64, v64, v220
	v_add_f32_e32 v65, v65, v221
	v_add_f32_e32 v68, 1.0, v68
	v_add_f32_e32 v69, 1.0, v69
	v_rcp_f32_e32 v68, v68
	v_rcp_f32_e32 v69, v69
	v_add_f32_e32 v70, v70, v218
	v_add_f32_e32 v71, v71, v219
	v_mul_f32_e32 v70, 0xbfb8aa3b, v70
	v_pk_mul_f32 v[68:69], v[68:69], s[38:39] op_sel_hi:[1,0]
	v_mul_f32_e32 v71, 0xbfb8aa3b, v71
	v_pk_mul_f32 v[72:73], v[224:225], v[68:69]
	v_exp_f32_e32 v70, v70
	v_pk_add_f32 v[146:147], v[72:73], v[72:73]
	v_mul_f32_e32 v68, 0x3fb8aa3b, v72
	v_fmamk_f32 v69, v146, 0x3ab60b61, v195
	v_exp_f32_e32 v68, v68
	v_fmaak_f32 v69, v146, v69, 0x3d2aaaab
	v_fmaak_f32 v69, v146, v69, 0x3e2aaaab
	v_exp_f32_e32 v71, v71
	v_fma_f32 v69, v146, v69, 0.5
	v_fma_f32 v69, v146, v69, 1.0
	v_mul_f32_e64 v69, v69, -v146
	v_fma_f32 v72, -v68, v68, 1.0
	v_cmp_lt_f32_e64 s[12:13], s84, v146
	v_add_f32_e32 v70, 1.0, v70
	v_add_f32_e32 v71, 1.0, v71
	v_cndmask_b32_e64 v69, v72, v69, s[12:13]
	v_sqrt_f32_e32 v72, v69
	v_mul_f32_e32 v69, 0x3fb8aa3b, v73
	v_fmamk_f32 v73, v147, 0x3ab60b61, v195
	v_rcp_f32_e32 v70, v70
	v_rcp_f32_e32 v71, v71
	v_exp_f32_e32 v69, v69
	v_fmaak_f32 v73, v147, v73, 0x3d2aaaab
	v_fmaak_f32 v73, v147, v73, 0x3e2aaaab
	v_fma_f32 v73, v147, v73, 0.5
	v_fma_f32 v73, v147, v73, 1.0
	v_pk_mul_f32 v[70:71], v[70:71], s[38:39] op_sel_hi:[1,0]
	v_cmp_lt_f32_e64 s[8:9], s84, v147
	v_mul_f32_e64 v73, v73, -v147
	v_fma_f32 v146, -v69, v69, 1.0
	v_pk_mul_f32 v[74:75], v[226:227], v[70:71]
	v_cndmask_b32_e64 v73, v146, v73, s[8:9]
	v_pk_add_f32 v[146:147], v[74:75], v[74:75]
	v_mul_f32_e32 v70, 0x3fb8aa3b, v74
	v_fmamk_f32 v71, v146, 0x3ab60b61, v195
	v_exp_f32_e32 v70, v70
	v_fmaak_f32 v71, v146, v71, 0x3d2aaaab
	v_fmaak_f32 v71, v146, v71, 0x3e2aaaab
	v_fma_f32 v71, v146, v71, 0.5
	v_fma_f32 v71, v146, v71, 1.0
	v_mul_f32_e64 v71, v71, -v146
	v_fma_f32 v74, -v70, v70, 1.0
	v_cmp_lt_f32_e64 s[12:13], s84, v146
	v_add_f32_e32 v66, v66, v222
	v_add_f32_e32 v67, v67, v223
	v_cndmask_b32_e64 v71, v74, v71, s[12:13]
	v_sqrt_f32_e32 v74, v71
	v_mul_f32_e32 v71, 0x3fb8aa3b, v75
	v_fmamk_f32 v75, v147, 0x3ab60b61, v195
	v_mul_f32_e32 v64, 0xbfb8aa3b, v64
	v_mul_f32_e32 v65, 0xbfb8aa3b, v65
	v_mul_f32_e32 v66, 0xbfb8aa3b, v66
	v_mul_f32_e32 v67, 0xbfb8aa3b, v67
	v_exp_f32_e32 v71, v71
	v_fmaak_f32 v75, v147, v75, 0x3d2aaaab
	v_exp_f32_e32 v64, v64
	v_exp_f32_e32 v65, v65
	v_exp_f32_e32 v66, v66
	v_exp_f32_e32 v67, v67
	v_fmaak_f32 v75, v147, v75, 0x3e2aaaab
	v_fma_f32 v75, v147, v75, 0.5
	v_fma_f32 v75, v147, v75, 1.0
	v_cmp_lt_f32_e64 s[8:9], s84, v147
	v_mul_f32_e64 v75, v75, -v147
	v_fma_f32 v146, -v71, v71, 1.0
	v_add_f32_e32 v64, 1.0, v64
	v_add_f32_e32 v65, 1.0, v65
	v_add_f32_e32 v66, 1.0, v66
	v_add_f32_e32 v67, 1.0, v67
	v_cndmask_b32_e64 v75, v146, v75, s[8:9]
	v_rcp_f32_e32 v64, v64
	v_rcp_f32_e32 v65, v65
	v_sqrt_f32_e32 v73, v73
	v_rcp_f32_e32 v66, v66
	v_rcp_f32_e32 v67, v67
	v_sqrt_f32_e32 v75, v75
	v_pk_mul_f32 v[64:65], v[64:65], v[72:73]
	v_pk_mul_f32 v[66:67], v[66:67], v[74:75]
	v_pk_mul_f32 v[72:73], v[64:65], v[174:175]
	v_pk_mul_f32 v[74:75], v[66:67], v[172:173]
	v_add3_u32 v66, s60, v176, v144
	v_lshl_add_u64 v[64:65], v[142:143], 0, s[24:25]
	ds_write_b128 v66, v[68:71] offset:8192
	ds_write_b128 v66, v[72:75] offset:24576
	v_lshlrev_b64 v[64:65], 2, v[64:65]
	v_lshl_add_u64 v[68:69], s[2:3], 0, v[64:65]
	s_mov_b64 s[2:3], s[48:49]
	v_bitop3_b32 v67, v166, v164, 2 bitop3:0x36
	v_lshl_add_u64 v[72:73], s[2:3], 0, v[64:65]
	s_mov_b64 s[2:3], s[74:75]
	s_add_u32 s2, s2, s30
	s_addc_u32 s3, s3, 0
	v_lshl_add_u64 v[142:143], s[2:3], 0, v[144:145]
	v_add_co_u32_e64 v142, s[8:9], s37, v142
	v_lshlrev_b32_e32 v67, 4, v67
	s_nop 0
	v_addc_co_u32_e64 v143, s[8:9], 0, v143, s[8:9]
	v_add3_u32 v67, v167, v67, v165
	ds_read_b64 v[142:143], v67
	s_mov_b64 s[2:3], s[44:45]
	s_waitcnt lgkmcnt(0)
	v_lshlrev_b32_e32 v168, 16, v142
	v_and_b32_e32 v169, 0xffff0000, v142
	v_lshlrev_b32_e32 v142, 16, v143
	v_and_b32_e32 v143, 0xffff0000, v143
	v_add_f32_e32 v60, v60, v228
	v_mul_f32_e32 v60, 0xbfb8aa3b, v60
	v_exp_f32_e32 v60, v60
	v_add_f32_e32 v62, v62, v230
	v_add_f32_e32 v56, v56, v232
	v_mul_f32_e32 v56, 0xbfb8aa3b, v56
	v_exp_f32_e32 v56, v56
	v_add_f32_e32 v58, v58, v234
	v_mul_f32_e32 v58, 0xbfb8aa3b, v58
	v_exp_f32_e32 v58, v58
	v_add_f32_e32 v56, 1.0, v56
	v_rcp_f32_e32 v68, v56
	v_add_f32_e32 v56, v61, v229
	v_mul_f32_e32 v56, 0xbfb8aa3b, v56
	v_exp_f32_e32 v56, v56
	v_add_f32_e32 v60, 1.0, v60
	v_rcp_f32_e32 v60, v60
	v_add_f32_e32 v58, 1.0, v58
	v_add_f32_e32 v56, 1.0, v56
	v_rcp_f32_e32 v61, v56
	v_add_f32_e32 v56, v57, v233
	v_mul_f32_e32 v56, 0xbfb8aa3b, v56
	v_exp_f32_e32 v56, v56
	v_rcp_f32_e32 v70, v58
	v_add_f32_e32 v58, v63, v231
	v_mul_f32_e32 v58, 0xbfb8aa3b, v58
	v_add_f32_e32 v56, 1.0, v56
	v_rcp_f32_e32 v69, v56
	v_pk_mul_f32 v[56:57], v[60:61], s[38:39] op_sel_hi:[1,0]
	v_exp_f32_e32 v58, v58
	v_pk_mul_f32 v[60:61], v[236:237], v[56:57]
	v_mul_f32_e32 v62, 0xbfb8aa3b, v62
	v_pk_add_f32 v[72:73], v[60:61], v[60:61]
	v_mul_f32_e32 v56, 0x3fb8aa3b, v60
	v_fmamk_f32 v57, v72, 0x3ab60b61, v195
	v_exp_f32_e32 v56, v56
	v_fmaak_f32 v57, v72, v57, 0x3d2aaaab
	v_exp_f32_e32 v62, v62
	v_fmaak_f32 v57, v72, v57, 0x3e2aaaab
	v_add_f32_e32 v58, 1.0, v58
	v_fma_f32 v57, v72, v57, 0.5
	v_rcp_f32_e32 v63, v58
	v_add_f32_e32 v58, v59, v235
	v_fma_f32 v57, v72, v57, 1.0
	v_mul_f32_e32 v58, 0xbfb8aa3b, v58
	v_mul_f32_e64 v57, v57, -v72
	v_fma_f32 v60, -v56, v56, 1.0
	v_cmp_lt_f32_e64 s[12:13], s84, v72
	v_add_f32_e32 v62, 1.0, v62
	v_exp_f32_e32 v58, v58
	v_cndmask_b32_e64 v57, v60, v57, s[12:13]
	v_rcp_f32_e32 v62, v62
	v_sqrt_f32_e32 v60, v57
	v_mul_f32_e32 v57, 0x3fb8aa3b, v61
	v_fmamk_f32 v61, v73, 0x3ab60b61, v195
	v_fmaak_f32 v61, v73, v61, 0x3d2aaaab
	v_fmaak_f32 v61, v73, v61, 0x3e2aaaab
	v_add_f32_e32 v58, 1.0, v58
	v_fma_f32 v61, v73, v61, 0.5
	v_rcp_f32_e32 v71, v58
	v_pk_mul_f32 v[58:59], v[62:63], s[38:39] op_sel_hi:[1,0]
	v_fma_f32 v61, v73, v61, 1.0
	v_pk_mul_f32 v[62:63], v[238:239], v[58:59]
	v_cmp_lt_f32_e64 s[8:9], s84, v73
	v_mul_f32_e64 v61, v61, -v73
	v_pk_add_f32 v[72:73], v[62:63], v[62:63]
	v_mul_f32_e32 v58, 0x3fb8aa3b, v62
	v_fmamk_f32 v59, v72, 0x3ab60b61, v195
	v_exp_f32_e32 v58, v58
	v_fmaak_f32 v59, v72, v59, 0x3d2aaaab
	v_fmaak_f32 v59, v72, v59, 0x3e2aaaab
	v_fma_f32 v59, v72, v59, 0.5
	v_fma_f32 v59, v72, v59, 1.0
	v_mul_f32_e64 v59, v59, -v72
	v_fma_f32 v62, -v58, v58, 1.0
	v_cmp_lt_f32_e64 s[12:13], s84, v72
	v_exp_f32_e32 v57, v57
	s_nop 0
	v_cndmask_b32_e64 v59, v62, v59, s[12:13]
	v_sqrt_f32_e32 v62, v59
	v_mul_f32_e32 v59, 0x3fb8aa3b, v63
	v_fmamk_f32 v63, v73, 0x3ab60b61, v195
	v_exp_f32_e32 v59, v59
	v_fmaak_f32 v63, v73, v63, 0x3d2aaaab
	v_fmaak_f32 v63, v73, v63, 0x3e2aaaab
	v_fma_f32 v63, v73, v63, 0.5
	v_fma_f32 v67, -v57, v57, 1.0
	v_fma_f32 v63, v73, v63, 1.0
	v_cndmask_b32_e64 v61, v67, v61, s[8:9]
	v_cmp_lt_f32_e64 s[8:9], s84, v73
	v_mul_f32_e64 v63, v63, -v73
	v_fma_f32 v67, -v59, v59, 1.0
	v_cndmask_b32_e64 v63, v67, v63, s[8:9]
	v_sqrt_f32_e32 v61, v61
	v_sqrt_f32_e32 v63, v63
	v_bitop3_b32 v67, v166, v164, 4 bitop3:0x36
	v_lshlrev_b32_e32 v67, 4, v67
	v_pk_mul_f32 v[60:61], v[68:69], v[60:61]
	v_pk_mul_f32 v[62:63], v[70:71], v[62:63]
	v_pk_mul_f32 v[60:61], v[60:61], v[168:169]
	v_pk_mul_f32 v[62:63], v[62:63], v[142:143]
	ds_write_b128 v66, v[56:59] offset:8256
	ds_write_b128 v66, v[60:63] offset:24640
	v_add3_u32 v67, v167, v67, v165
	v_lshl_add_u64 v[56:57], s[2:3], 0, v[64:65]
	s_mov_b64 s[2:3], s[48:49]
	s_waitcnt vmcnt(0) lgkmcnt(0)
	v_add_f32_e32 v52, v52, v240
	v_lshl_add_u64 v[60:61], s[2:3], 0, v[64:65]
	s_mov_b64 s[2:3], s[74:75]
	s_add_u32 s2, s2, s30
	s_addc_u32 s3, s3, 0
	v_lshl_add_u64 v[68:69], s[2:3], 0, v[144:145]
	v_add_co_u32_e64 v68, s[8:9], s37, v68
	v_mul_f32_e32 v52, 0xbfb8aa3b, v52
	s_nop 0
	v_addc_co_u32_e64 v69, s[8:9], 0, v69, s[8:9]
	v_exp_f32_e32 v52, v52
	v_add_f32_e32 v54, v54, v242
	v_mul_f32_e32 v54, 0xbfb8aa3b, v54
	v_exp_f32_e32 v54, v54
	v_add_f32_e32 v52, 1.0, v52
	v_rcp_f32_e32 v52, v52
	ds_read_b64 v[72:73], v67
	v_add_f32_e32 v54, 1.0, v54
	v_rcp_f32_e32 v54, v54
	s_mov_b64 s[2:3], s[44:45]
	s_waitcnt lgkmcnt(0)
	v_lshlrev_b32_e32 v74, 16, v72
	v_and_b32_e32 v75, 0xffff0000, v72
	v_lshlrev_b32_e32 v72, 16, v73
	v_and_b32_e32 v73, 0xffff0000, v73
	v_add_f32_e32 v48, v48, v244
	v_mul_f32_e32 v48, 0xbfb8aa3b, v48
	v_exp_f32_e32 v48, v48
	v_add_f32_e32 v50, v50, v246
	v_mul_f32_e32 v50, 0xbfb8aa3b, v50
	v_exp_f32_e32 v50, v50
	v_add_f32_e32 v48, 1.0, v48
	v_rcp_f32_e32 v56, v48
	v_add_f32_e32 v48, v53, v241
	v_mul_f32_e32 v48, 0xbfb8aa3b, v48
	v_exp_f32_e32 v48, v48
	v_add_f32_e32 v50, 1.0, v50
	v_rcp_f32_e32 v58, v50
	v_add_f32_e32 v50, v55, v243
	v_add_f32_e32 v48, 1.0, v48
	v_rcp_f32_e32 v53, v48
	v_add_f32_e32 v48, v49, v245
	v_mul_f32_e32 v48, 0xbfb8aa3b, v48
	v_exp_f32_e32 v48, v48
	v_mul_f32_e32 v50, 0xbfb8aa3b, v50
	v_exp_f32_e32 v50, v50
	v_add_f32_e32 v48, 1.0, v48
	v_rcp_f32_e32 v57, v48
	v_pk_mul_f32 v[48:49], v[52:53], s[38:39] op_sel_hi:[1,0]
	v_add_f32_e32 v50, 1.0, v50
	v_pk_mul_f32 v[52:53], v[248:249], v[48:49]
	v_rcp_f32_e32 v55, v50
	v_pk_add_f32 v[60:61], v[52:53], v[52:53]
	v_mul_f32_e32 v48, 0x3fb8aa3b, v52
	v_fmamk_f32 v49, v60, 0x3ab60b61, v195
	v_exp_f32_e32 v48, v48
	v_fmaak_f32 v49, v60, v49, 0x3d2aaaab
	v_fmaak_f32 v49, v60, v49, 0x3e2aaaab
	v_fma_f32 v49, v60, v49, 0.5
	v_fma_f32 v49, v60, v49, 1.0
	v_add_f32_e32 v50, v51, v247
	v_mul_f32_e64 v49, v49, -v60
	v_fma_f32 v52, -v48, v48, 1.0
	v_cmp_lt_f32_e64 s[12:13], s84, v60
	v_mul_f32_e32 v50, 0xbfb8aa3b, v50
	v_exp_f32_e32 v50, v50
	v_cndmask_b32_e64 v49, v52, v49, s[12:13]
	v_sqrt_f32_e32 v52, v49
	v_mul_f32_e32 v49, 0x3fb8aa3b, v53
	v_fmamk_f32 v53, v61, 0x3ab60b61, v195
	v_exp_f32_e32 v49, v49
	v_fmaak_f32 v53, v61, v53, 0x3d2aaaab
	v_fmaak_f32 v53, v61, v53, 0x3e2aaaab
	v_fma_f32 v53, v61, v53, 0.5
	v_add_f32_e32 v50, 1.0, v50
	v_fma_f32 v53, v61, v53, 1.0
	v_rcp_f32_e32 v59, v50
	v_pk_mul_f32 v[50:51], v[54:55], s[38:39] op_sel_hi:[1,0]
	v_cmp_lt_f32_e64 s[8:9], s84, v61
	v_mul_f32_e64 v53, v53, -v61
	v_fma_f32 v60, -v49, v49, 1.0
	v_pk_mul_f32 v[54:55], v[250:251], v[50:51]
	v_cndmask_b32_e64 v53, v60, v53, s[8:9]
	v_pk_add_f32 v[60:61], v[54:55], v[54:55]
	v_mul_f32_e32 v50, 0x3fb8aa3b, v54
	v_fmamk_f32 v51, v60, 0x3ab60b61, v195
	v_exp_f32_e32 v50, v50
	v_fmaak_f32 v51, v60, v51, 0x3d2aaaab
	v_fmaak_f32 v51, v60, v51, 0x3e2aaaab
	v_fma_f32 v51, v60, v51, 0.5
	v_fma_f32 v51, v60, v51, 1.0
	v_mul_f32_e64 v51, v51, -v60
	v_fma_f32 v54, -v50, v50, 1.0
	v_cmp_lt_f32_e64 s[12:13], s84, v60
	v_cmp_lt_f32_e64 s[8:9], s84, v61
	v_sqrt_f32_e32 v53, v53
	v_cndmask_b32_e64 v51, v54, v51, s[12:13]
	v_sqrt_f32_e32 v54, v51
	v_mul_f32_e32 v51, 0x3fb8aa3b, v55
	v_fmamk_f32 v55, v61, 0x3ab60b61, v195
	v_exp_f32_e32 v51, v51
	v_fmaak_f32 v55, v61, v55, 0x3d2aaaab
	v_fmaak_f32 v55, v61, v55, 0x3e2aaaab
	v_fma_f32 v55, v61, v55, 0.5
	v_fma_f32 v55, v61, v55, 1.0
	v_mul_f32_e64 v55, v55, -v61
	v_fma_f32 v60, -v51, v51, 1.0
	v_cndmask_b32_e64 v55, v60, v55, s[8:9]
	v_sqrt_f32_e32 v55, v55
	v_pk_mul_f32 v[52:53], v[56:57], v[52:53]
	v_bitop3_b32 v60, v166, v164, 6 bitop3:0x36
	v_pk_mul_f32 v[52:53], v[52:53], v[74:75]
	v_pk_mul_f32 v[54:55], v[58:59], v[54:55]
	v_lshlrev_b32_e32 v60, 4, v60
	v_pk_mul_f32 v[54:55], v[54:55], v[72:73]
	ds_write_b128 v66, v[48:51] offset:8320
	ds_write_b128 v66, v[52:55] offset:24704
	v_add3_u32 v60, v167, v60, v165
	v_lshl_add_u64 v[48:49], s[2:3], 0, v[64:65]
	s_mov_b64 s[2:3], s[48:49]
	s_waitcnt vmcnt(0) lgkmcnt(0)
	v_add_f32_e32 v12, v12, v178
	v_lshl_add_u64 v[52:53], s[2:3], 0, v[64:65]
	s_mov_b64 s[2:3], s[74:75]
	s_add_u32 s2, s2, s30
	s_addc_u32 s3, s3, 0
	v_lshl_add_u64 v[56:57], s[2:3], 0, v[144:145]
	v_add_co_u32_e64 v56, s[8:9], s37, v56
	v_mul_f32_e32 v12, 0xbfb8aa3b, v12
	s_nop 0
	v_addc_co_u32_e64 v57, s[8:9], 0, v57, s[8:9]
	flat_load_dwordx4 v[56:59], v[56:57] offset:2240
	v_exp_f32_e32 v12, v12
	v_add_f32_e32 v14, v14, v180
	v_mul_f32_e32 v14, 0xbfb8aa3b, v14
	v_exp_f32_e32 v14, v14
	v_add_f32_e32 v12, 1.0, v12
	v_rcp_f32_e32 v12, v12
	ds_read_b64 v[60:61], v60
	v_add_f32_e32 v14, 1.0, v14
	v_rcp_f32_e32 v14, v14
	s_waitcnt lgkmcnt(0)
	v_lshlrev_b32_e32 v62, 16, v60
	v_and_b32_e32 v63, 0xffff0000, v60
	v_lshlrev_b32_e32 v60, 16, v61
	v_and_b32_e32 v61, 0xffff0000, v61
	s_waitcnt vmcnt(0)
	v_add_f32_e32 v8, v8, v182
	v_mul_f32_e32 v8, 0xbfb8aa3b, v8
	v_exp_f32_e32 v8, v8
	v_add_f32_e32 v10, v10, v184
	v_mul_f32_e32 v10, 0xbfb8aa3b, v10
	v_exp_f32_e32 v10, v10
	v_add_f32_e32 v8, 1.0, v8
	v_rcp_f32_e32 v48, v8
	v_add_f32_e32 v8, v13, v179
	v_mul_f32_e32 v8, 0xbfb8aa3b, v8
	v_exp_f32_e32 v8, v8
	v_add_f32_e32 v10, 1.0, v10
	v_rcp_f32_e32 v50, v10
	v_add_f32_e32 v10, v15, v181
	v_add_f32_e32 v8, 1.0, v8
	v_rcp_f32_e32 v13, v8
	v_add_f32_e32 v8, v9, v183
	v_mul_f32_e32 v8, 0xbfb8aa3b, v8
	v_exp_f32_e32 v8, v8
	v_mul_f32_e32 v10, 0xbfb8aa3b, v10
	v_exp_f32_e32 v10, v10
	v_add_f32_e32 v8, 1.0, v8
	v_rcp_f32_e32 v49, v8
	v_pk_mul_f32 v[8:9], v[12:13], s[38:39] op_sel_hi:[1,0]
	v_add_f32_e32 v10, 1.0, v10
	v_pk_mul_f32 v[12:13], v[56:57], v[8:9]
	v_rcp_f32_e32 v15, v10
	v_pk_add_f32 v[52:53], v[12:13], v[12:13]
	v_mul_f32_e32 v8, 0x3fb8aa3b, v12
	v_fmamk_f32 v9, v52, 0x3ab60b61, v195
	v_exp_f32_e32 v8, v8
	v_fmaak_f32 v9, v52, v9, 0x3d2aaaab
	v_fmaak_f32 v9, v52, v9, 0x3e2aaaab
	v_fma_f32 v9, v52, v9, 0.5
	v_fma_f32 v9, v52, v9, 1.0
	v_add_f32_e32 v10, v11, v185
	v_mul_f32_e64 v9, v9, -v52
	v_fma_f32 v12, -v8, v8, 1.0
	v_cmp_lt_f32_e64 s[12:13], s84, v52
	v_mul_f32_e32 v10, 0xbfb8aa3b, v10
	v_exp_f32_e32 v10, v10
	v_cndmask_b32_e64 v9, v12, v9, s[12:13]
	v_sqrt_f32_e32 v12, v9
	v_mul_f32_e32 v9, 0x3fb8aa3b, v13
	v_fmamk_f32 v13, v53, 0x3ab60b61, v195
	v_exp_f32_e32 v9, v9
	v_fmaak_f32 v13, v53, v13, 0x3d2aaaab
	v_fmaak_f32 v13, v53, v13, 0x3e2aaaab
	v_fma_f32 v13, v53, v13, 0.5
	v_add_f32_e32 v10, 1.0, v10
	v_fma_f32 v13, v53, v13, 1.0
	v_rcp_f32_e32 v51, v10
	v_pk_mul_f32 v[10:11], v[14:15], s[38:39] op_sel_hi:[1,0]
	v_cmp_lt_f32_e64 s[8:9], s84, v53
	v_mul_f32_e64 v13, v13, -v53
	v_fma_f32 v52, -v9, v9, 1.0
	v_pk_mul_f32 v[14:15], v[58:59], v[10:11]
	v_cndmask_b32_e64 v13, v52, v13, s[8:9]
	v_pk_add_f32 v[52:53], v[14:15], v[14:15]
	v_mul_f32_e32 v10, 0x3fb8aa3b, v14
	v_fmamk_f32 v11, v52, 0x3ab60b61, v195
	v_exp_f32_e32 v10, v10
	v_fmaak_f32 v11, v52, v11, 0x3d2aaaab
	v_fmaak_f32 v11, v52, v11, 0x3e2aaaab
	v_fma_f32 v11, v52, v11, 0.5
	v_fma_f32 v11, v52, v11, 1.0
	v_mul_f32_e64 v11, v11, -v52
	v_fma_f32 v14, -v10, v10, 1.0
	v_cmp_lt_f32_e64 s[12:13], s84, v52
	v_cmp_lt_f32_e64 s[8:9], s84, v53
	v_sqrt_f32_e32 v13, v13
	v_cndmask_b32_e64 v11, v14, v11, s[12:13]
	v_sqrt_f32_e32 v14, v11
	v_mul_f32_e32 v11, 0x3fb8aa3b, v15
	v_fmamk_f32 v15, v53, 0x3ab60b61, v195
	v_exp_f32_e32 v11, v11
	v_fmaak_f32 v15, v53, v15, 0x3d2aaaab
	v_fmaak_f32 v15, v53, v15, 0x3e2aaaab
	v_fma_f32 v15, v53, v15, 0.5
	v_fma_f32 v15, v53, v15, 1.0
	v_mul_f32_e64 v15, v15, -v53
	v_fma_f32 v52, -v11, v11, 1.0
	v_cndmask_b32_e64 v15, v52, v15, s[8:9]
	v_sqrt_f32_e32 v15, v15
	v_pk_mul_f32 v[12:13], v[48:49], v[12:13]
	v_cmp_gt_i32_e64 s[8:9], 3, v161
	v_pk_mul_f32 v[12:13], v[12:13], v[62:63]
	v_pk_mul_f32 v[14:15], v[50:51], v[14:15]
	s_nop 0
	v_pk_mul_f32 v[14:15], v[14:15], v[60:61]
	ds_write_b128 v66, v[8:11] offset:8384
	ds_write_b128 v66, v[12:15] offset:24768
	v_and_b32_e32 v8, 63, v163
	v_lshlrev_b32_e32 v10, 2, v8
	v_lshl_or_b32 v9, v161, 12, v10
	v_add_u32_e32 v12, s60, v9
	s_waitcnt lgkmcnt(0)
	s_barrier
	ds_read2st64_b32 v[14:15], v12 offset0:46 offset1:47
	ds_read2st64_b32 v[48:49], v12 offset0:110 offset1:111
	ds_read2st64_b32 v[50:51], v12 offset0:44 offset1:45
	ds_read2st64_b32 v[52:53], v12 offset0:108 offset1:109
	v_and_b32_e32 v11, 0x1fffffc0, v162
	s_waitcnt lgkmcnt(2)
	v_fma_f32 v9, 0, v15, v49
	v_fmac_f32_e32 v48, v9, v14
	s_waitcnt lgkmcnt(0)
	v_fma_f32 v9, v48, v51, v53
	ds_read2st64_b32 v[48:49], v12 offset0:42 offset1:43
	ds_read2st64_b32 v[54:55], v12 offset0:106 offset1:107
	v_fmac_f32_e32 v52, v9, v50
	v_mul_f32_e32 v14, v15, v14
	v_mov_b32_e32 v62, v51
	s_waitcnt lgkmcnt(0)
	v_fma_f32 v9, v52, v49, v55
	ds_read2st64_b32 v[52:53], v12 offset0:40 offset1:41
	ds_read2st64_b32 v[56:57], v12 offset0:104 offset1:105
	v_fmac_f32_e32 v54, v9, v48
	s_waitcnt lgkmcnt(1)
	v_mov_b32_e32 v66, v53
	s_waitcnt lgkmcnt(0)
	v_fma_f32 v9, v54, v53, v57
	ds_read2st64_b32 v[54:55], v12 offset0:38 offset1:39
	ds_read2st64_b32 v[58:59], v12 offset0:102 offset1:103
	v_fmac_f32_e32 v56, v9, v52
	v_mul_f32_e32 v9, v14, v51
	v_mov_b32_e32 v68, v53
	s_waitcnt lgkmcnt(1)
	v_mov_b32_e32 v63, v54
	s_waitcnt lgkmcnt(0)
	v_fmac_f32_e32 v59, v56, v55
	ds_read2st64_b32 v[56:57], v12 offset0:36 offset1:37
	ds_read2st64_b32 v[60:61], v12 offset0:100 offset1:101
	v_mov_b32_e32 v15, v59
	v_mov_b32_e32 v51, v58
	v_pk_fma_f32 v[14:15], v[14:15], v[62:63], v[50:51]
	v_mul_f32_e32 v58, v9, v50
	v_mov_b32_e32 v59, v15
	v_mov_b32_e32 v14, v49
	s_waitcnt lgkmcnt(1)
	v_mov_b32_e32 v15, v57
	v_pk_mul_f32 v[50:51], v[58:59], v[14:15]
	s_waitcnt lgkmcnt(0)
	v_mov_b32_e32 v49, v61
	v_pk_mul_f32 v[50:51], v[50:51], v[48:49]
	v_pk_fma_f32 v[14:15], v[58:59], v[14:15], v[48:49]
	ds_read2st64_b32 v[48:49], v12 offset0:34 offset1:35
	ds_read2st64_b32 v[58:59], v12 offset0:98 offset1:99
	ds_read2st64_b32 v[62:63], v12 offset0:32 offset1:33
	ds_read2st64_b32 v[64:65], v12 offset0:96 offset1:97
	v_mov_b32_e32 v14, v50
	v_mov_b32_e32 v69, v56
	v_pk_mul_f32 v[50:51], v[50:51], v[66:67]
	v_mov_b32_e32 v53, v60
	v_pk_mul_f32 v[50:51], v[50:51], v[52:53]
	v_pk_fma_f32 v[14:15], v[14:15], v[68:69], v[52:53]
	v_lshl_add_u32 v9, v8, 3, s60
	v_mov_b32_e32 v51, v15
	v_mov_b32_e32 v14, v55
	s_waitcnt lgkmcnt(3)
	v_mov_b32_e32 v15, v49
	v_pk_mul_f32 v[52:53], v[50:51], v[14:15]
	s_waitcnt lgkmcnt(2)
	v_mov_b32_e32 v55, v59
	v_pk_mul_f32 v[52:53], v[52:53], v[54:55]
	v_pk_fma_f32 v[14:15], v[50:51], v[14:15], v[54:55]
	v_mov_b32_e32 v50, v57
	v_mov_b32_e32 v14, v52
	v_mov_b32_e32 v54, v57
	v_mov_b32_e32 v55, v48
	v_pk_mul_f32 v[50:51], v[52:53], v[50:51]
	v_mov_b32_e32 v57, v58
	v_pk_mul_f32 v[50:51], v[50:51], v[56:57]
	v_pk_fma_f32 v[14:15], v[14:15], v[54:55], v[56:57]
	v_lshl_add_u32 v11, v11, 3, v9
	v_mov_b32_e32 v51, v15
	v_mov_b32_e32 v14, v49
	s_waitcnt lgkmcnt(1)
	v_mov_b32_e32 v15, v63
	v_pk_mul_f32 v[52:53], v[50:51], v[14:15]
	s_waitcnt lgkmcnt(0)
	v_mov_b32_e32 v49, v65
	v_pk_mul_f32 v[52:53], v[52:53], v[48:49]
	v_pk_fma_f32 v[14:15], v[50:51], v[14:15], v[48:49]
	v_mov_b32_e32 v48, v63
	v_mov_b32_e32 v14, v52
	v_mov_b32_e32 v50, v63
	v_mov_b32_e32 v51, v62
	v_pk_mul_f32 v[48:49], v[52:53], v[48:49]
	v_mov_b32_e32 v63, v64
	v_pk_mul_f32 v[48:49], v[48:49], v[62:63]
	v_pk_fma_f32 v[14:15], v[14:15], v[50:51], v[62:63]
	s_nop 0
	v_mov_b32_e32 v49, v15
	ds_write_b64 v11, v[48:49] offset:40960
	v_sub_u32_e32 v11, v9, v10
	s_waitcnt lgkmcnt(0)
	s_barrier
	ds_read_b32 v11, v11 offset:43264
	s_and_saveexec_b64 s[2:3], s[8:9]
	s_cbranch_execz .LBB0_367
	ds_read_b64 v[14:15], v9 offset:42496
	s_waitcnt lgkmcnt(0)
	v_fmac_f32_e32 v15, v11, v14
	v_mov_b32_e32 v11, v15
	s_or_b64 exec, exec, s[2:3]
	v_cmp_gt_i32_e64 s[8:9], 2, v161
	s_and_saveexec_b64 s[2:3], s[8:9]
	s_cbranch_execnz .LBB0_368

.LBB0_383:
	s_bfe_u32 s25, s0, 0x60003
	s_mov_b64 s[6:7], s[74:75]
	s_waitcnt lgkmcnt(0)
	s_barrier
	s_lshl_b32 s28, s25, 6
	v_lshlrev_b32_e32 v144, 1, v78
	s_add_i32 s29, s28, -2
	v_lshl_add_u64 v[8:9], s[6:7], 0, v[144:145]
	s_mov_b64 s[6:7], 0x91e0000
	s_ashr_i32 s26, s0, 9
	v_lshl_add_u64 v[48:49], v[8:9], 0, s[6:7]
	v_add_u32_e32 v50, s29, v79
	s_waitcnt vmcnt(0)
	v_mov_b64_e32 v[14:15], v[6:7]
	s_lshl_b32 s27, s26, 12
	v_cmp_gt_u32_e32 vcc, s67, v50
	v_mov_b64_e32 v[12:13], v[4:5]
	v_mov_b64_e32 v[10:11], v[2:3]
	v_mov_b64_e32 v[8:9], v[0:1]
	v_mov_b64_e32 v[216:217], 0
	v_mov_b64_e32 v[218:219], 0
	s_and_saveexec_b64 s[6:7], vcc
	v_or_b32_e32 v232, s27, v50
	v_ashrrev_i32_e32 v233, 31, v232
	v_lshlrev_b64 v[232:233], 10, v[232:233]
	v_lshl_add_u64 v[232:233], v[48:49], 0, v[232:233]
	global_load_dwordx4 v[216:219], v[232:233], off
	s_or_b64 exec, exec, s[6:7]
	v_add_u32_e32 v51, 1, v50
	v_cmp_gt_u32_e32 vcc, s67, v51
	v_mov_b64_e32 v[220:221], 0
	v_mov_b64_e32 v[222:223], 0
	s_and_saveexec_b64 s[6:7], vcc
	v_or_b32_e32 v234, s27, v51
	v_ashrrev_i32_e32 v235, 31, v234
	v_lshlrev_b64 v[234:235], 10, v[234:235]
	v_lshl_add_u64 v[234:235], v[48:49], 0, v[234:235]
	global_load_dwordx4 v[220:223], v[234:235], off
	s_or_b64 exec, exec, s[6:7]
	v_add_u32_e32 v51, s28, v79
	v_cmp_gt_u32_e32 vcc, s67, v51
	v_mov_b64_e32 v[224:225], 0
	v_mov_b64_e32 v[226:227], 0
	s_and_saveexec_b64 s[6:7], vcc
	v_or_b32_e32 v236, s27, v51
	v_ashrrev_i32_e32 v237, 31, v236
	v_lshlrev_b64 v[236:237], 10, v[236:237]
	v_lshl_add_u64 v[236:237], v[48:49], 0, v[236:237]
	global_load_dwordx4 v[224:227], v[236:237], off
	s_or_b64 exec, exec, s[6:7]
	v_add_u32_e32 v50, 3, v50
	v_cmp_gt_u32_e32 vcc, s67, v50
	v_mov_b64_e32 v[228:229], 0
	v_mov_b64_e32 v[230:231], 0
	s_and_saveexec_b64 s[6:7], vcc
	v_or_b32_e32 v238, s27, v50
	v_ashrrev_i32_e32 v239, 31, v238
	v_lshlrev_b64 v[238:239], 10, v[238:239]
	v_lshl_add_u64 v[238:239], v[48:49], 0, v[238:239]
	global_load_dwordx4 v[228:231], v[238:239], off
	s_or_b64 exec, exec, s[6:7]
	s_waitcnt vmcnt(0)
	v_lshlrev_b32_e32 v52, 16, v216
	v_and_b32_e32 v53, 0xffff0000, v216
	v_lshlrev_b32_e32 v8, 16, v217
	v_and_b32_e32 v9, 0xffff0000, v217
	v_lshlrev_b32_e32 v12, 16, v218
	v_and_b32_e32 v13, 0xffff0000, v218
	v_lshlrev_b32_e32 v10, 16, v219
	v_and_b32_e32 v11, 0xffff0000, v219
	v_pk_fma_f32 v[14:15], v[22:23], v[10:11], v[6:7]
	v_pk_fma_f32 v[12:13], v[20:21], v[12:13], v[4:5]
	v_pk_fma_f32 v[10:11], v[18:19], v[8:9], v[2:3]
	v_pk_fma_f32 v[8:9], v[16:17], v[52:53], v[0:1]
	v_lshlrev_b32_e32 v56, 16, v220
	v_and_b32_e32 v57, 0xffff0000, v220
	v_lshlrev_b32_e32 v52, 16, v221
	v_and_b32_e32 v53, 0xffff0000, v221
	v_lshlrev_b32_e32 v58, 16, v222
	v_and_b32_e32 v59, 0xffff0000, v222
	v_lshlrev_b32_e32 v54, 16, v223
	v_and_b32_e32 v55, 0xffff0000, v223
	v_pk_fma_f32 v[14:15], v[30:31], v[54:55], v[14:15]
	v_pk_fma_f32 v[12:13], v[28:29], v[58:59], v[12:13]
	v_pk_fma_f32 v[10:11], v[26:27], v[52:53], v[10:11]
	v_pk_fma_f32 v[8:9], v[24:25], v[56:57], v[8:9]
	v_lshlrev_b32_e32 v56, 16, v224
	v_and_b32_e32 v57, 0xffff0000, v224
	v_lshlrev_b32_e32 v52, 16, v225
	v_and_b32_e32 v53, 0xffff0000, v225
	v_lshlrev_b32_e32 v58, 16, v226
	v_and_b32_e32 v59, 0xffff0000, v226
	v_lshlrev_b32_e32 v54, 16, v227
	v_and_b32_e32 v55, 0xffff0000, v227
	v_pk_fma_f32 v[14:15], v[38:39], v[54:55], v[14:15]
	v_pk_fma_f32 v[12:13], v[36:37], v[58:59], v[12:13]
	v_pk_fma_f32 v[10:11], v[34:35], v[52:53], v[10:11]
	v_pk_fma_f32 v[8:9], v[32:33], v[56:57], v[8:9]
	v_lshlrev_b32_e32 v54, 16, v228
	v_and_b32_e32 v55, 0xffff0000, v228
	v_lshlrev_b32_e32 v50, 16, v229
	v_and_b32_e32 v51, 0xffff0000, v229
	v_lshlrev_b32_e32 v56, 16, v230
	v_and_b32_e32 v57, 0xffff0000, v230
	v_lshlrev_b32_e32 v52, 16, v231
	v_and_b32_e32 v53, 0xffff0000, v231
	v_pk_fma_f32 v[14:15], v[46:47], v[52:53], v[14:15]
	v_pk_fma_f32 v[12:13], v[44:45], v[56:57], v[12:13]
	v_pk_fma_f32 v[10:11], v[42:43], v[50:51], v[10:11]
	v_pk_fma_f32 v[8:9], v[40:41], v[54:55], v[8:9]
	v_cvt_pk_bf16_f32 v8, v8, v9
	v_cvt_pk_bf16_f32 v9, v10, v11
	v_cvt_pk_bf16_f32 v10, v12, v13
	v_cvt_pk_bf16_f32 v11, v14, v15
	ds_write_b128 v81, v[8:11]
	v_add_u32_e32 v50, s29, v80
	v_mov_b64_e32 v[14:15], v[6:7]
	v_cmp_gt_u32_e32 vcc, s67, v50
	v_mov_b64_e32 v[12:13], v[4:5]
	v_mov_b64_e32 v[10:11], v[2:3]
	v_mov_b64_e32 v[8:9], v[0:1]
	v_mov_b64_e32 v[216:217], 0
	v_mov_b64_e32 v[218:219], 0
	s_and_saveexec_b64 s[6:7], vcc
	v_or_b32_e32 v232, s27, v50
	v_ashrrev_i32_e32 v233, 31, v232
	v_lshlrev_b64 v[232:233], 10, v[232:233]
	v_lshl_add_u64 v[232:233], v[48:49], 0, v[232:233]
	global_load_dwordx4 v[216:219], v[232:233], off
	s_or_b64 exec, exec, s[6:7]
	v_add_u32_e32 v51, 1, v50
	v_cmp_gt_u32_e32 vcc, s67, v51
	v_mov_b64_e32 v[220:221], 0
	v_mov_b64_e32 v[222:223], 0
	s_and_saveexec_b64 s[6:7], vcc
	v_or_b32_e32 v234, s27, v51
	v_ashrrev_i32_e32 v235, 31, v234
	v_lshlrev_b64 v[234:235], 10, v[234:235]
	v_lshl_add_u64 v[234:235], v[48:49], 0, v[234:235]
	global_load_dwordx4 v[220:223], v[234:235], off
	s_or_b64 exec, exec, s[6:7]
	v_add_u32_e32 v51, s28, v80
	v_cmp_gt_u32_e32 vcc, s67, v51
	v_mov_b64_e32 v[224:225], 0
	v_mov_b64_e32 v[226:227], 0
	s_and_saveexec_b64 s[6:7], vcc
	v_or_b32_e32 v236, s27, v51
	v_ashrrev_i32_e32 v237, 31, v236
	v_lshlrev_b64 v[236:237], 10, v[236:237]
	v_lshl_add_u64 v[236:237], v[48:49], 0, v[236:237]
	global_load_dwordx4 v[224:227], v[236:237], off
	s_or_b64 exec, exec, s[6:7]
	v_add_u32_e32 v50, 3, v50
	v_cmp_gt_u32_e32 vcc, s67, v50
	v_mov_b64_e32 v[228:229], 0
	v_mov_b64_e32 v[230:231], 0
	s_and_saveexec_b64 s[6:7], vcc
	v_or_b32_e32 v238, s27, v50
	v_ashrrev_i32_e32 v239, 31, v238
	v_lshlrev_b64 v[238:239], 10, v[238:239]
	v_lshl_add_u64 v[238:239], v[48:49], 0, v[238:239]
	global_load_dwordx4 v[228:231], v[238:239], off
	s_or_b64 exec, exec, s[6:7]
	s_waitcnt vmcnt(0)
	v_lshlrev_b32_e32 v52, 16, v216
	v_and_b32_e32 v53, 0xffff0000, v216
	v_lshlrev_b32_e32 v8, 16, v217
	v_and_b32_e32 v9, 0xffff0000, v217
	v_lshlrev_b32_e32 v12, 16, v218
	v_and_b32_e32 v13, 0xffff0000, v218
	v_lshlrev_b32_e32 v10, 16, v219
	v_and_b32_e32 v11, 0xffff0000, v219
	v_pk_fma_f32 v[14:15], v[22:23], v[10:11], v[6:7]
	v_pk_fma_f32 v[12:13], v[20:21], v[12:13], v[4:5]
	v_pk_fma_f32 v[10:11], v[18:19], v[8:9], v[2:3]
	v_pk_fma_f32 v[8:9], v[16:17], v[52:53], v[0:1]
	v_lshlrev_b32_e32 v56, 16, v220
	v_and_b32_e32 v57, 0xffff0000, v220
	v_lshlrev_b32_e32 v52, 16, v221
	v_and_b32_e32 v53, 0xffff0000, v221
	v_lshlrev_b32_e32 v58, 16, v222
	v_and_b32_e32 v59, 0xffff0000, v222
	v_lshlrev_b32_e32 v54, 16, v223
	v_and_b32_e32 v55, 0xffff0000, v223
	v_pk_fma_f32 v[14:15], v[30:31], v[54:55], v[14:15]
	v_pk_fma_f32 v[12:13], v[28:29], v[58:59], v[12:13]
	v_pk_fma_f32 v[10:11], v[26:27], v[52:53], v[10:11]
	v_pk_fma_f32 v[8:9], v[24:25], v[56:57], v[8:9]
	v_lshlrev_b32_e32 v56, 16, v224
	v_and_b32_e32 v57, 0xffff0000, v224
	v_lshlrev_b32_e32 v52, 16, v225
	v_and_b32_e32 v53, 0xffff0000, v225
	v_lshlrev_b32_e32 v58, 16, v226
	v_and_b32_e32 v59, 0xffff0000, v226
	v_lshlrev_b32_e32 v54, 16, v227
	v_and_b32_e32 v55, 0xffff0000, v227
	v_pk_fma_f32 v[14:15], v[38:39], v[54:55], v[14:15]
	v_pk_fma_f32 v[12:13], v[36:37], v[58:59], v[12:13]
	v_pk_fma_f32 v[10:11], v[34:35], v[52:53], v[10:11]
	v_pk_fma_f32 v[8:9], v[32:33], v[56:57], v[8:9]
	v_lshlrev_b32_e32 v52, 16, v228
	v_and_b32_e32 v53, 0xffff0000, v228
	v_lshlrev_b32_e32 v48, 16, v229
	v_and_b32_e32 v49, 0xffff0000, v229
	v_lshlrev_b32_e32 v54, 16, v230
	v_and_b32_e32 v55, 0xffff0000, v230
	v_lshlrev_b32_e32 v50, 16, v231
	v_and_b32_e32 v51, 0xffff0000, v231
	v_pk_fma_f32 v[14:15], v[46:47], v[50:51], v[14:15]
	v_pk_fma_f32 v[12:13], v[44:45], v[54:55], v[12:13]
	v_pk_fma_f32 v[10:11], v[42:43], v[48:49], v[10:11]
	v_pk_fma_f32 v[8:9], v[40:41], v[52:53], v[8:9]
	v_mov_b32_e32 v83, v191
	v_cvt_pk_bf16_f32 v8, v8, v9
	v_cvt_pk_bf16_f32 v9, v10, v11
	v_cvt_pk_bf16_f32 v10, v12, v13
	v_cvt_pk_bf16_f32 v11, v14, v15
	ds_write_b128 v82, v[8:11]
	s_waitcnt lgkmcnt(0)
	s_barrier
	v_mov_b32_e32 v85, v191
	v_and_b32_e32 v87, 15, v83
	v_lshrrev_b32_e32 v96, 4, v83
	v_bfe_u32 v97, v83, 4, 2
	s_mov_b64 s[6:7], s[74:75]
	v_bfe_u32 v86, v83, 1, 3
	v_ashrrev_i32_e32 v84, 6, v83
	v_lshlrev_b32_e32 v76, 7, v87
	v_bitop3_b32 v8, v96, v86, 3 bitop3:0x6c
	v_bitop3_b32 v13, v97, v86, 4 bitop3:0x36
	v_lshl_or_b32 v12, v84, 11, v76
	v_lshlrev_b32_e32 v8, 4, v8
	v_lshlrev_b32_e32 v13, 4, v13
	s_add_u32 s6, s6, s2
	v_add3_u32 v8, s60, v8, v12
	v_add3_u32 v12, s60, v13, v12
	s_addc_u32 s7, s7, 0
	v_lshlrev_b32_e32 v144, 4, v97
	ds_read_b128 v[8:11], v8
	ds_read_b128 v[72:75], v12
	v_lshl_add_u64 v[12:13], s[6:7], 0, v[144:145]
	s_mov_b64 s[6:7], 0x3980000
	v_lshl_add_u64 v[92:93], v[12:13], 0, s[6:7]
	s_mov_b64 s[6:7], 0x39a0000
	v_mov_b32_e32 v77, v145
	v_lshl_add_u64 v[94:95], v[12:13], 0, s[6:7]
	v_lshl_add_u64 v[60:61], v[92:93], 0, v[76:77]
	v_lshl_add_u64 v[62:63], v[94:95], 0, v[76:77]
	s_mov_b64 s[98:99], 0x1000
	v_lshl_add_u64 v[180:181], v[60:61], 0, s[98:99]
	v_lshl_add_u64 v[182:183], v[62:63], 0, s[98:99]
	global_load_dwordx4 v[104:107], v[180:181], off offset:-4096
	global_load_dwordx4 v[108:111], v[182:183], off offset:-4096
	global_load_dwordx4 v[112:115], v[180:181], off offset:-4032
	global_load_dwordx4 v[116:119], v[182:183], off offset:-4032
	global_load_dwordx4 v[120:123], v[180:181], off offset:-2048
	global_load_dwordx4 v[124:127], v[182:183], off offset:-2048
	global_load_dwordx4 v[128:131], v[180:181], off offset:-1984
	global_load_dwordx4 v[132:135], v[182:183], off offset:-1984
	global_load_dwordx4 v[136:139], v[180:181], off
	global_load_dwordx4 v[140:143], v[182:183], off
	global_load_dwordx4 v[156:159], v[180:181], off offset:64
	global_load_dwordx4 v[160:163], v[182:183], off offset:64
	global_load_dwordx4 v[164:167], v[180:181], off offset:2048
	global_load_dwordx4 v[168:171], v[182:183], off offset:2048
	global_load_dwordx4 v[172:175], v[180:181], off offset:2112
	global_load_dwordx4 v[176:179], v[182:183], off offset:2112
	v_lshrrev_b32_e32 v98, 1, v83
	v_readlane_b32 s36, v254, 22
	v_readlane_b32 s40, v254, 26
	v_readlane_b32 s41, v254, 27
	s_mov_b64 s[6:7], s[40:41]
	v_readlane_b32 s44, v254, 30
	v_readlane_b32 s45, v254, 31
	s_mov_b32 s27, 0x122e6000
	s_mov_b32 s28, 0xc1000000
	v_readlane_b32 s37, v254, 23
	v_readlane_b32 s38, v254, 24
	v_readlane_b32 s39, v254, 25
	v_readlane_b32 s42, v254, 28
	v_readlane_b32 s43, v254, 29
	v_readlane_b32 s46, v254, 32
	v_readlane_b32 s47, v254, 33
	v_readlane_b32 s48, v254, 34
	v_readlane_b32 s49, v254, 35
	v_readlane_b32 s50, v254, 36
	v_readlane_b32 s51, v254, 37
	v_lshlrev_b32_e32 v154, 2, v97
	v_or_b32_e32 v154, s8, v154
	v_ashrrev_i32_e32 v155, 31, v154
	v_lshlrev_b64 v[154:155], 2, v[154:155]
	s_add_u32 s98, s74, s3
	s_addc_u32 s99, s75, 0
	s_add_u32 s98, s98, 0x122e6000
	s_addc_u32 s99, s99, 0
	v_lshl_add_u64 v[184:185], s[98:99], 0, v[144:145]
	v_lshl_add_u64 v[180:181], s[40:41], 0, v[154:155]
	v_lshl_add_u64 v[146:147], s[44:45], 0, v[154:155]
	global_load_dwordx4 v[216:219], v[180:181], off
	global_load_dwordx4 v[220:223], v[146:147], off
	global_load_dwordx4 v[224:227], v[184:185], off
	global_load_dwordx4 v[228:231], v[180:181], off offset:64
	global_load_dwordx4 v[232:235], v[146:147], off offset:64
	global_load_dwordx4 v[236:239], v[184:185], off offset:64
	global_load_dwordx4 v[240:243], v[180:181], off offset:128
	global_load_dwordx4 v[244:247], v[146:147], off offset:128
	global_load_dwordx4 v[248:251], v[184:185], off offset:128
	global_load_dwordx4 v[180:183], v[180:181], off offset:192
	global_load_dwordx4 v[146:149], v[146:147], off offset:192
	s_waitcnt vmcnt(0) lgkmcnt(0)
	v_mfma_f32_16x16x32_bf16 v[12:15], v[104:107], v[8:11], 0
	v_mfma_f32_16x16x32_bf16 v[48:51], v[108:111], v[8:11], 0
	v_mfma_f32_16x16x32_bf16 v[68:71], v[112:115], v[72:75], v[12:15]
	v_mfma_f32_16x16x32_bf16 v[64:67], v[116:119], v[72:75], v[48:51]
	s_nop 4
	v_mfma_f32_16x16x32_bf16 v[12:15], v[120:123], v[8:11], 0
	v_mfma_f32_16x16x32_bf16 v[48:51], v[124:127], v[8:11], 0
	v_mfma_f32_16x16x32_bf16 v[60:63], v[128:131], v[72:75], v[12:15]
	s_nop 5
	v_or_b32_e32 v12, 0x1000, v76
	v_mov_b32_e32 v13, v145
	v_lshl_add_u64 v[52:53], v[92:93], 0, v[12:13]
	v_mfma_f32_16x16x32_bf16 v[56:59], v[132:135], v[72:75], v[48:51]
	v_lshl_add_u64 v[88:89], v[94:95], 0, v[12:13]
	s_nop 0
	s_nop 0
	s_nop 0
	v_mfma_f32_16x16x32_bf16 v[12:15], v[136:139], v[8:11], 0
	v_mfma_f32_16x16x32_bf16 v[48:51], v[140:143], v[8:11], 0
	v_mfma_f32_16x16x32_bf16 v[52:55], v[156:159], v[72:75], v[12:15]
	s_nop 5
	v_or_b32_e32 v12, 0x1800, v76
	v_mov_b32_e32 v13, v145
	v_lshl_add_u64 v[76:77], v[92:93], 0, v[12:13]
	v_mfma_f32_16x16x32_bf16 v[48:51], v[160:163], v[72:75], v[48:51]
	v_lshl_add_u64 v[92:93], v[94:95], 0, v[12:13]
	v_mfma_f32_16x16x32_bf16 v[12:15], v[164:167], v[8:11], 0
	v_mfma_f32_16x16x32_bf16 v[8:11], v[168:171], v[8:11], 0
	s_nop 0
	v_lshlrev_b32_e32 v76, 2, v97
	v_mov_b32_e32 v77, v145
	v_mfma_f32_16x16x32_bf16 v[12:15], v[172:175], v[72:75], v[12:15]
	v_bfe_u32 v88, v96, 1, 1
	v_mfma_f32_16x16x32_bf16 v[8:11], v[176:179], v[72:75], v[8:11]
	global_load_dwordx4 v[104:107], v[184:185], off offset:192
	v_lshl_or_b32 v72, v84, 4, v87
	v_lshlrev_b32_e32 v87, 7, v72
	v_and_b32_e32 v73, 8, v98
	v_lshlrev_b32_e32 v102, 8, v72
	v_or_b32_e32 v72, s8, v76
	v_add_u32_e32 v89, s60, v73
	v_ashrrev_i32_e32 v73, 31, v72
	v_lshlrev_b64 v[90:91], 2, v[72:73]
	v_lshl_add_u64 v[72:73], s[6:7], 0, v[90:91]
	s_mov_b64 s[6:7], s[44:45]
	v_bitop3_b32 v98, v88, v98, 7 bitop3:0x78
	v_lshl_add_u64 v[90:91], s[6:7], 0, v[90:91]
	s_mov_b64 s[6:7], s[74:75]
	s_add_u32 s6, s6, s3
	s_addc_u32 s7, s7, 0
	v_lshl_add_u64 v[94:95], s[6:7], 0, v[144:145]
	v_add_co_u32_e32 v94, vcc, s27, v94
	v_lshlrev_b32_e32 v98, 4, v98
	s_nop 0
	v_addc_co_u32_e32 v95, vcc, 0, v95, vcc
	v_add3_u32 v98, v89, v98, v87
	ds_read_b64 v[98:99], v98
	s_waitcnt lgkmcnt(0)
	v_lshlrev_b32_e32 v100, 16, v98
	v_and_b32_e32 v101, 0xffff0000, v98
	v_lshlrev_b32_e32 v98, 16, v99
	v_and_b32_e32 v99, 0xffff0000, v99
	v_add_f32_e32 v68, v68, v216
	v_add_f32_e32 v69, v69, v217
	v_mul_f32_e32 v68, 0xbfb8aa3b, v68
	v_mul_f32_e32 v69, 0xbfb8aa3b, v69
	v_exp_f32_e32 v68, v68
	v_exp_f32_e32 v69, v69
	v_add_f32_e32 v64, v64, v220
	v_add_f32_e32 v65, v65, v221
	v_add_f32_e32 v68, 1.0, v68
	v_add_f32_e32 v69, 1.0, v69
	v_rcp_f32_e32 v68, v68
	v_rcp_f32_e32 v69, v69
	v_add_f32_e32 v70, v70, v218
	v_add_f32_e32 v71, v71, v219
	v_mul_f32_e32 v70, 0xbfb8aa3b, v70
	v_pk_mul_f32 v[68:69], v[68:69], s[28:29] op_sel_hi:[1,0]
	v_mul_f32_e32 v71, 0xbfb8aa3b, v71
	v_pk_mul_f32 v[72:73], v[224:225], v[68:69]
	v_exp_f32_e32 v70, v70
	v_pk_add_f32 v[90:91], v[72:73], v[72:73]
	v_mul_f32_e32 v68, 0x3fb8aa3b, v72
	v_fmamk_f32 v69, v90, 0x3ab60b61, v195
	v_exp_f32_e32 v68, v68
	v_fmaak_f32 v69, v90, v69, 0x3d2aaaab
	v_fmaak_f32 v69, v90, v69, 0x3e2aaaab
	v_exp_f32_e32 v71, v71
	v_fma_f32 v69, v90, v69, 0.5
	v_fma_f32 v69, v90, v69, 1.0
	v_mul_f32_e64 v69, v69, -v90
	v_fma_f32 v72, -v68, v68, 1.0
	v_cmp_lt_f32_e64 s[6:7], s84, v90
	v_add_f32_e32 v70, 1.0, v70
	v_add_f32_e32 v71, 1.0, v71
	v_cndmask_b32_e64 v69, v72, v69, s[6:7]
	v_sqrt_f32_e32 v72, v69
	v_mul_f32_e32 v69, 0x3fb8aa3b, v73
	v_fmamk_f32 v73, v91, 0x3ab60b61, v195
	v_rcp_f32_e32 v70, v70
	v_rcp_f32_e32 v71, v71
	v_exp_f32_e32 v69, v69
	v_fmaak_f32 v73, v91, v73, 0x3d2aaaab
	v_fmaak_f32 v73, v91, v73, 0x3e2aaaab
	v_fma_f32 v73, v91, v73, 0.5
	v_fma_f32 v73, v91, v73, 1.0
	v_pk_mul_f32 v[70:71], v[70:71], s[28:29] op_sel_hi:[1,0]
	v_cmp_lt_f32_e32 vcc, s84, v91
	v_mul_f32_e64 v73, v73, -v91
	v_fma_f32 v90, -v69, v69, 1.0
	v_pk_mul_f32 v[74:75], v[226:227], v[70:71]
	v_cndmask_b32_e32 v73, v90, v73, vcc
	v_pk_add_f32 v[90:91], v[74:75], v[74:75]
	v_mul_f32_e32 v70, 0x3fb8aa3b, v74
	v_fmamk_f32 v71, v90, 0x3ab60b61, v195
	v_exp_f32_e32 v70, v70
	v_fmaak_f32 v71, v90, v71, 0x3d2aaaab
	v_fmaak_f32 v71, v90, v71, 0x3e2aaaab
	v_fma_f32 v71, v90, v71, 0.5
	v_fma_f32 v71, v90, v71, 1.0
	v_mul_f32_e64 v71, v71, -v90
	v_fma_f32 v74, -v70, v70, 1.0
	v_cmp_lt_f32_e64 s[6:7], s84, v90
	v_add_f32_e32 v66, v66, v222
	v_add_f32_e32 v67, v67, v223
	v_cndmask_b32_e64 v71, v74, v71, s[6:7]
	v_sqrt_f32_e32 v74, v71
	v_mul_f32_e32 v71, 0x3fb8aa3b, v75
	v_fmamk_f32 v75, v91, 0x3ab60b61, v195
	v_mul_f32_e32 v64, 0xbfb8aa3b, v64
	v_mul_f32_e32 v65, 0xbfb8aa3b, v65
	v_mul_f32_e32 v66, 0xbfb8aa3b, v66
	v_mul_f32_e32 v67, 0xbfb8aa3b, v67
	v_exp_f32_e32 v71, v71
	v_fmaak_f32 v75, v91, v75, 0x3d2aaaab
	v_exp_f32_e32 v64, v64
	v_exp_f32_e32 v65, v65
	v_exp_f32_e32 v66, v66
	v_exp_f32_e32 v67, v67
	v_fmaak_f32 v75, v91, v75, 0x3e2aaaab
	v_fma_f32 v75, v91, v75, 0.5
	v_fma_f32 v75, v91, v75, 1.0
	v_cmp_lt_f32_e32 vcc, s84, v91
	v_mul_f32_e64 v75, v75, -v91
	v_fma_f32 v90, -v71, v71, 1.0
	v_add_f32_e32 v64, 1.0, v64
	v_add_f32_e32 v65, 1.0, v65
	v_add_f32_e32 v66, 1.0, v66
	v_add_f32_e32 v67, 1.0, v67
	v_cndmask_b32_e32 v75, v90, v75, vcc
	v_rcp_f32_e32 v64, v64
	v_rcp_f32_e32 v65, v65
	v_sqrt_f32_e32 v73, v73
	v_rcp_f32_e32 v66, v66
	v_rcp_f32_e32 v67, v67
	v_sqrt_f32_e32 v75, v75
	v_pk_mul_f32 v[64:65], v[64:65], v[72:73]
	s_mov_b64 s[6:7], s[40:41]
	v_pk_mul_f32 v[72:73], v[64:65], v[100:101]
	v_pk_mul_f32 v[66:67], v[66:67], v[74:75]
	v_lshl_add_u64 v[64:65], v[76:77], 0, s[8:9]
	v_pk_mul_f32 v[74:75], v[66:67], v[98:99]
	v_add3_u32 v66, s60, v102, v144
	ds_write_b128 v66, v[68:71] offset:8192
	ds_write_b128 v66, v[72:75] offset:24576
	v_lshlrev_b64 v[64:65], 2, v[64:65]
	v_lshl_add_u64 v[68:69], s[6:7], 0, v[64:65]
	s_mov_b64 s[6:7], s[44:45]
	v_bitop3_b32 v67, v88, v86, 2 bitop3:0x36
	v_lshl_add_u64 v[72:73], s[6:7], 0, v[64:65]
	s_mov_b64 s[6:7], s[74:75]
	s_add_u32 s6, s6, s3
	s_addc_u32 s7, s7, 0
	v_lshl_add_u64 v[76:77], s[6:7], 0, v[144:145]
	v_add_co_u32_e32 v76, vcc, s27, v76
	v_lshlrev_b32_e32 v67, 4, v67
	s_nop 0
	v_addc_co_u32_e32 v77, vcc, 0, v77, vcc
	v_add3_u32 v67, v89, v67, v87
	ds_read_b64 v[76:77], v67
	s_waitcnt lgkmcnt(0)
	v_lshlrev_b32_e32 v94, 16, v76
	v_and_b32_e32 v95, 0xffff0000, v76
	v_lshlrev_b32_e32 v76, 16, v77
	v_and_b32_e32 v77, 0xffff0000, v77
	v_add_f32_e32 v60, v60, v228
	v_mul_f32_e32 v60, 0xbfb8aa3b, v60
	v_exp_f32_e32 v60, v60
	v_add_f32_e32 v62, v62, v230
	v_add_f32_e32 v56, v56, v232
	v_mul_f32_e32 v56, 0xbfb8aa3b, v56
	v_exp_f32_e32 v56, v56
	v_add_f32_e32 v58, v58, v234
	v_mul_f32_e32 v58, 0xbfb8aa3b, v58
	v_exp_f32_e32 v58, v58
	v_add_f32_e32 v56, 1.0, v56
	v_rcp_f32_e32 v68, v56
	v_add_f32_e32 v56, v61, v229
	v_mul_f32_e32 v56, 0xbfb8aa3b, v56
	v_exp_f32_e32 v56, v56
	v_add_f32_e32 v60, 1.0, v60
	v_rcp_f32_e32 v60, v60
	v_add_f32_e32 v58, 1.0, v58
	v_add_f32_e32 v56, 1.0, v56
	v_rcp_f32_e32 v61, v56
	v_add_f32_e32 v56, v57, v233
	v_mul_f32_e32 v56, 0xbfb8aa3b, v56
	v_exp_f32_e32 v56, v56
	v_rcp_f32_e32 v70, v58
	v_add_f32_e32 v58, v63, v231
	v_mul_f32_e32 v58, 0xbfb8aa3b, v58
	v_add_f32_e32 v56, 1.0, v56
	v_rcp_f32_e32 v69, v56
	v_pk_mul_f32 v[56:57], v[60:61], s[28:29] op_sel_hi:[1,0]
	v_exp_f32_e32 v58, v58
	v_pk_mul_f32 v[60:61], v[236:237], v[56:57]
	v_mul_f32_e32 v62, 0xbfb8aa3b, v62
	v_pk_add_f32 v[72:73], v[60:61], v[60:61]
	v_mul_f32_e32 v56, 0x3fb8aa3b, v60
	v_fmamk_f32 v57, v72, 0x3ab60b61, v195
	v_exp_f32_e32 v56, v56
	v_fmaak_f32 v57, v72, v57, 0x3d2aaaab
	v_exp_f32_e32 v62, v62
	v_fmaak_f32 v57, v72, v57, 0x3e2aaaab
	v_add_f32_e32 v58, 1.0, v58
	v_fma_f32 v57, v72, v57, 0.5
	v_rcp_f32_e32 v63, v58
	v_add_f32_e32 v58, v59, v235
	v_fma_f32 v57, v72, v57, 1.0
	v_mul_f32_e32 v58, 0xbfb8aa3b, v58
	v_mul_f32_e64 v57, v57, -v72
	v_fma_f32 v60, -v56, v56, 1.0
	v_cmp_lt_f32_e64 s[6:7], s84, v72
	v_add_f32_e32 v62, 1.0, v62
	v_exp_f32_e32 v58, v58
	v_cndmask_b32_e64 v57, v60, v57, s[6:7]
	v_rcp_f32_e32 v62, v62
	v_sqrt_f32_e32 v60, v57
	v_mul_f32_e32 v57, 0x3fb8aa3b, v61
	v_fmamk_f32 v61, v73, 0x3ab60b61, v195
	v_fmaak_f32 v61, v73, v61, 0x3d2aaaab
	v_fmaak_f32 v61, v73, v61, 0x3e2aaaab
	v_add_f32_e32 v58, 1.0, v58
	v_fma_f32 v61, v73, v61, 0.5
	v_rcp_f32_e32 v71, v58
	v_pk_mul_f32 v[58:59], v[62:63], s[28:29] op_sel_hi:[1,0]
	v_fma_f32 v61, v73, v61, 1.0
	v_pk_mul_f32 v[62:63], v[238:239], v[58:59]
	v_cmp_lt_f32_e32 vcc, s84, v73
	v_mul_f32_e64 v61, v61, -v73
	v_pk_add_f32 v[72:73], v[62:63], v[62:63]
	v_mul_f32_e32 v58, 0x3fb8aa3b, v62
	v_fmamk_f32 v59, v72, 0x3ab60b61, v195
	v_exp_f32_e32 v58, v58
	v_fmaak_f32 v59, v72, v59, 0x3d2aaaab
	v_fmaak_f32 v59, v72, v59, 0x3e2aaaab
	v_fma_f32 v59, v72, v59, 0.5
	v_fma_f32 v59, v72, v59, 1.0
	v_mul_f32_e64 v59, v59, -v72
	v_fma_f32 v62, -v58, v58, 1.0
	v_cmp_lt_f32_e64 s[6:7], s84, v72
	v_exp_f32_e32 v57, v57
	s_nop 0
	v_cndmask_b32_e64 v59, v62, v59, s[6:7]
	v_sqrt_f32_e32 v62, v59
	v_mul_f32_e32 v59, 0x3fb8aa3b, v63
	v_fmamk_f32 v63, v73, 0x3ab60b61, v195
	v_exp_f32_e32 v59, v59
	v_fmaak_f32 v63, v73, v63, 0x3d2aaaab
	v_fmaak_f32 v63, v73, v63, 0x3e2aaaab
	v_fma_f32 v63, v73, v63, 0.5
	v_fma_f32 v67, -v57, v57, 1.0
	v_fma_f32 v63, v73, v63, 1.0
	v_cndmask_b32_e32 v61, v67, v61, vcc
	v_cmp_lt_f32_e32 vcc, s84, v73
	v_mul_f32_e64 v63, v63, -v73
	v_fma_f32 v67, -v59, v59, 1.0
	v_cndmask_b32_e32 v63, v67, v63, vcc
	v_sqrt_f32_e32 v61, v61
	v_sqrt_f32_e32 v63, v63
	s_mov_b64 s[6:7], s[40:41]
	v_bitop3_b32 v67, v88, v86, 4 bitop3:0x36
	v_pk_mul_f32 v[60:61], v[68:69], v[60:61]
	v_pk_mul_f32 v[62:63], v[70:71], v[62:63]
	v_pk_mul_f32 v[60:61], v[60:61], v[94:95]
	v_pk_mul_f32 v[62:63], v[62:63], v[76:77]
	ds_write_b128 v66, v[56:59] offset:8256
	ds_write_b128 v66, v[60:63] offset:24640
	v_lshlrev_b32_e32 v67, 4, v67
	v_lshl_add_u64 v[56:57], s[6:7], 0, v[64:65]
	s_mov_b64 s[6:7], s[44:45]
	v_add3_u32 v67, v89, v67, v87
	v_lshl_add_u64 v[60:61], s[6:7], 0, v[64:65]
	s_mov_b64 s[6:7], s[74:75]
	s_add_u32 s6, s6, s3
	s_addc_u32 s7, s7, 0
	v_lshl_add_u64 v[68:69], s[6:7], 0, v[144:145]
	v_add_co_u32_e32 v68, vcc, s27, v68
	ds_read_b64 v[72:73], v67
	s_nop 0
	v_addc_co_u32_e32 v69, vcc, 0, v69, vcc
	s_waitcnt lgkmcnt(0)
	v_lshlrev_b32_e32 v74, 16, v72
	v_and_b32_e32 v75, 0xffff0000, v72
	v_lshlrev_b32_e32 v72, 16, v73
	v_and_b32_e32 v73, 0xffff0000, v73
	v_add_f32_e32 v52, v52, v240
	v_mul_f32_e32 v52, 0xbfb8aa3b, v52
	v_exp_f32_e32 v52, v52
	v_add_f32_e32 v54, v54, v242
	v_add_f32_e32 v48, v48, v244
	v_mul_f32_e32 v48, 0xbfb8aa3b, v48
	v_exp_f32_e32 v48, v48
	v_add_f32_e32 v50, v50, v246
	v_mul_f32_e32 v50, 0xbfb8aa3b, v50
	v_add_f32_e32 v52, 1.0, v52
	v_add_f32_e32 v48, 1.0, v48
	v_rcp_f32_e32 v56, v48
	v_add_f32_e32 v48, v53, v241
	v_mul_f32_e32 v48, 0xbfb8aa3b, v48
	v_exp_f32_e32 v48, v48
	v_exp_f32_e32 v50, v50
	v_rcp_f32_e32 v52, v52
	v_mul_f32_e32 v54, 0xbfb8aa3b, v54
	v_add_f32_e32 v48, 1.0, v48
	v_rcp_f32_e32 v53, v48
	v_add_f32_e32 v48, v49, v245
	v_mul_f32_e32 v48, 0xbfb8aa3b, v48
	v_exp_f32_e32 v48, v48
	v_add_f32_e32 v50, 1.0, v50
	v_rcp_f32_e32 v58, v50
	v_add_f32_e32 v50, v55, v243
	v_add_f32_e32 v48, 1.0, v48
	v_rcp_f32_e32 v57, v48
	v_pk_mul_f32 v[48:49], v[52:53], s[28:29] op_sel_hi:[1,0]
	v_mul_f32_e32 v50, 0xbfb8aa3b, v50
	v_pk_mul_f32 v[52:53], v[248:249], v[48:49]
	v_exp_f32_e32 v50, v50
	v_pk_add_f32 v[60:61], v[52:53], v[52:53]
	v_mul_f32_e32 v48, 0x3fb8aa3b, v52
	v_fmamk_f32 v49, v60, 0x3ab60b61, v195
	v_exp_f32_e32 v48, v48
	v_fmaak_f32 v49, v60, v49, 0x3d2aaaab
	v_fmaak_f32 v49, v60, v49, 0x3e2aaaab
	v_exp_f32_e32 v54, v54
	v_fma_f32 v49, v60, v49, 0.5
	v_add_f32_e32 v50, 1.0, v50
	v_fma_f32 v49, v60, v49, 1.0
	v_rcp_f32_e32 v55, v50
	v_add_f32_e32 v50, v51, v247
	v_mul_f32_e64 v49, v49, -v60
	v_fma_f32 v52, -v48, v48, 1.0
	v_cmp_lt_f32_e64 s[6:7], s84, v60
	v_mul_f32_e32 v50, 0xbfb8aa3b, v50
	v_add_f32_e32 v54, 1.0, v54
	v_cndmask_b32_e64 v49, v52, v49, s[6:7]
	v_exp_f32_e32 v50, v50
	v_sqrt_f32_e32 v52, v49
	v_mul_f32_e32 v49, 0x3fb8aa3b, v53
	v_fmamk_f32 v53, v61, 0x3ab60b61, v195
	v_rcp_f32_e32 v54, v54
	v_exp_f32_e32 v49, v49
	v_fmaak_f32 v53, v61, v53, 0x3d2aaaab
	v_fmaak_f32 v53, v61, v53, 0x3e2aaaab
	v_fma_f32 v53, v61, v53, 0.5
	v_add_f32_e32 v50, 1.0, v50
	v_fma_f32 v53, v61, v53, 1.0
	v_rcp_f32_e32 v59, v50
	v_pk_mul_f32 v[50:51], v[54:55], s[28:29] op_sel_hi:[1,0]
	v_cmp_lt_f32_e32 vcc, s84, v61
	v_mul_f32_e64 v53, v53, -v61
	v_fma_f32 v60, -v49, v49, 1.0
	v_pk_mul_f32 v[54:55], v[250:251], v[50:51]
	v_cndmask_b32_e32 v53, v60, v53, vcc
	v_pk_add_f32 v[60:61], v[54:55], v[54:55]
	v_mul_f32_e32 v50, 0x3fb8aa3b, v54
	v_fmamk_f32 v51, v60, 0x3ab60b61, v195
	v_exp_f32_e32 v50, v50
	v_fmaak_f32 v51, v60, v51, 0x3d2aaaab
	v_fmaak_f32 v51, v60, v51, 0x3e2aaaab
	v_fma_f32 v51, v60, v51, 0.5
	v_fma_f32 v51, v60, v51, 1.0
	v_mul_f32_e64 v51, v51, -v60
	v_fma_f32 v54, -v50, v50, 1.0
	v_cmp_lt_f32_e64 s[6:7], s84, v60
	v_cmp_lt_f32_e32 vcc, s84, v61
	v_sqrt_f32_e32 v53, v53
	v_cndmask_b32_e64 v51, v54, v51, s[6:7]
	v_sqrt_f32_e32 v54, v51
	v_mul_f32_e32 v51, 0x3fb8aa3b, v55
	v_fmamk_f32 v55, v61, 0x3ab60b61, v195
	v_exp_f32_e32 v51, v51
	v_fmaak_f32 v55, v61, v55, 0x3d2aaaab
	v_fmaak_f32 v55, v61, v55, 0x3e2aaaab
	v_fma_f32 v55, v61, v55, 0.5
	v_fma_f32 v55, v61, v55, 1.0
	v_mul_f32_e64 v55, v55, -v61
	v_fma_f32 v60, -v51, v51, 1.0
	v_cndmask_b32_e32 v55, v60, v55, vcc
	v_sqrt_f32_e32 v55, v55
	v_pk_mul_f32 v[52:53], v[56:57], v[52:53]
	s_mov_b64 s[6:7], s[40:41]
	v_pk_mul_f32 v[52:53], v[52:53], v[74:75]
	v_pk_mul_f32 v[54:55], v[58:59], v[54:55]
	v_bitop3_b32 v60, v88, v86, 6 bitop3:0x36
	v_pk_mul_f32 v[54:55], v[54:55], v[72:73]
	ds_write_b128 v66, v[48:51] offset:8320
	ds_write_b128 v66, v[52:55] offset:24704
	v_lshlrev_b32_e32 v60, 4, v60
	v_lshl_add_u64 v[48:49], s[6:7], 0, v[64:65]
	s_mov_b64 s[6:7], s[44:45]
	v_add3_u32 v60, v89, v60, v87
	v_lshl_add_u64 v[52:53], s[6:7], 0, v[64:65]
	s_mov_b64 s[6:7], s[74:75]
	s_add_u32 s6, s6, s3
	s_addc_u32 s7, s7, 0
	v_lshl_add_u64 v[56:57], s[6:7], 0, v[144:145]
	v_add_co_u32_e32 v56, vcc, s27, v56
	ds_read_b64 v[60:61], v60
	s_nop 0
	v_addc_co_u32_e32 v57, vcc, 0, v57, vcc
	s_waitcnt lgkmcnt(0)
	v_lshlrev_b32_e32 v62, 16, v60
	v_and_b32_e32 v63, 0xffff0000, v60
	v_lshlrev_b32_e32 v60, 16, v61
	v_and_b32_e32 v61, 0xffff0000, v61
	s_waitcnt vmcnt(0)
	v_add_f32_e32 v12, v12, v180
	v_mul_f32_e32 v12, 0xbfb8aa3b, v12
	v_exp_f32_e32 v12, v12
	v_add_f32_e32 v14, v14, v182
	v_add_f32_e32 v8, v8, v146
	v_mul_f32_e32 v8, 0xbfb8aa3b, v8
	v_exp_f32_e32 v8, v8
	v_add_f32_e32 v10, v10, v148
	v_mul_f32_e32 v10, 0xbfb8aa3b, v10
	v_add_f32_e32 v12, 1.0, v12
	v_add_f32_e32 v8, 1.0, v8
	v_rcp_f32_e32 v48, v8
	v_add_f32_e32 v8, v13, v181
	v_mul_f32_e32 v8, 0xbfb8aa3b, v8
	v_exp_f32_e32 v8, v8
	v_exp_f32_e32 v10, v10
	v_rcp_f32_e32 v12, v12
	v_mul_f32_e32 v14, 0xbfb8aa3b, v14
	v_add_f32_e32 v8, 1.0, v8
	v_rcp_f32_e32 v13, v8
	v_add_f32_e32 v8, v9, v147
	v_mul_f32_e32 v8, 0xbfb8aa3b, v8
	v_exp_f32_e32 v8, v8
	v_add_f32_e32 v10, 1.0, v10
	v_rcp_f32_e32 v50, v10
	v_add_f32_e32 v10, v15, v183
	v_add_f32_e32 v8, 1.0, v8
	v_rcp_f32_e32 v49, v8
	v_pk_mul_f32 v[8:9], v[12:13], s[28:29] op_sel_hi:[1,0]
	v_mul_f32_e32 v10, 0xbfb8aa3b, v10
	v_pk_mul_f32 v[12:13], v[104:105], v[8:9]
	v_exp_f32_e32 v10, v10
	v_pk_add_f32 v[52:53], v[12:13], v[12:13]
	v_mul_f32_e32 v8, 0x3fb8aa3b, v12
	v_fmamk_f32 v9, v52, 0x3ab60b61, v195
	v_exp_f32_e32 v8, v8
	v_fmaak_f32 v9, v52, v9, 0x3d2aaaab
	v_fmaak_f32 v9, v52, v9, 0x3e2aaaab
	v_exp_f32_e32 v14, v14
	v_fma_f32 v9, v52, v9, 0.5
	v_add_f32_e32 v10, 1.0, v10
	v_fma_f32 v9, v52, v9, 1.0
	v_rcp_f32_e32 v15, v10
	v_add_f32_e32 v10, v11, v149
	v_mul_f32_e64 v9, v9, -v52
	v_fma_f32 v12, -v8, v8, 1.0
	v_cmp_lt_f32_e64 s[6:7], s84, v52
	v_mul_f32_e32 v10, 0xbfb8aa3b, v10
	v_add_f32_e32 v14, 1.0, v14
	v_cndmask_b32_e64 v9, v12, v9, s[6:7]
	v_exp_f32_e32 v10, v10
	v_sqrt_f32_e32 v12, v9
	v_mul_f32_e32 v9, 0x3fb8aa3b, v13
	v_fmamk_f32 v13, v53, 0x3ab60b61, v195
	v_rcp_f32_e32 v14, v14
	v_exp_f32_e32 v9, v9
	v_fmaak_f32 v13, v53, v13, 0x3d2aaaab
	v_fmaak_f32 v13, v53, v13, 0x3e2aaaab
	v_fma_f32 v13, v53, v13, 0.5
	v_add_f32_e32 v10, 1.0, v10
	v_fma_f32 v13, v53, v13, 1.0
	v_rcp_f32_e32 v51, v10
	v_pk_mul_f32 v[10:11], v[14:15], s[28:29] op_sel_hi:[1,0]
	v_cmp_lt_f32_e32 vcc, s84, v53
	v_mul_f32_e64 v13, v13, -v53
	v_fma_f32 v52, -v9, v9, 1.0
	v_pk_mul_f32 v[14:15], v[106:107], v[10:11]
	v_cndmask_b32_e32 v13, v52, v13, vcc
	v_pk_add_f32 v[52:53], v[14:15], v[14:15]
	v_mul_f32_e32 v10, 0x3fb8aa3b, v14
	v_fmamk_f32 v11, v52, 0x3ab60b61, v195
	v_exp_f32_e32 v10, v10
	v_fmaak_f32 v11, v52, v11, 0x3d2aaaab
	v_fmaak_f32 v11, v52, v11, 0x3e2aaaab
	v_fma_f32 v11, v52, v11, 0.5
	v_fma_f32 v11, v52, v11, 1.0
	v_mul_f32_e64 v11, v11, -v52
	v_fma_f32 v14, -v10, v10, 1.0
	v_cmp_lt_f32_e64 s[6:7], s84, v52
	v_cmp_lt_f32_e32 vcc, s84, v53
	v_sqrt_f32_e32 v13, v13
	v_cndmask_b32_e64 v11, v14, v11, s[6:7]
	v_sqrt_f32_e32 v14, v11
	v_mul_f32_e32 v11, 0x3fb8aa3b, v15
	v_fmamk_f32 v15, v53, 0x3ab60b61, v195
	v_exp_f32_e32 v11, v11
	v_fmaak_f32 v15, v53, v15, 0x3d2aaaab
	v_fmaak_f32 v15, v53, v15, 0x3e2aaaab
	v_fma_f32 v15, v53, v15, 0.5
	v_fma_f32 v15, v53, v15, 1.0
	v_mul_f32_e64 v15, v15, -v53
	v_fma_f32 v52, -v11, v11, 1.0
	v_cndmask_b32_e32 v15, v52, v15, vcc
	v_sqrt_f32_e32 v15, v15
	v_pk_mul_f32 v[12:13], v[48:49], v[12:13]
	v_cmp_gt_u32_e32 vcc, 64, v83
	v_pk_mul_f32 v[12:13], v[12:13], v[62:63]
	v_pk_mul_f32 v[14:15], v[50:51], v[14:15]
	s_nop 0
	v_pk_mul_f32 v[14:15], v[14:15], v[60:61]
	ds_write_b128 v66, v[8:11] offset:8384
	ds_write_b128 v66, v[12:15] offset:24768
	v_and_b32_e32 v8, 63, v85
	v_lshlrev_b32_e32 v9, 2, v8
	v_lshl_or_b32 v9, v84, 12, v9
	v_add_u32_e32 v9, s60, v9
	s_waitcnt lgkmcnt(0)
	s_barrier
	ds_read2st64_b32 v[10:11], v9 offset0:32 offset1:33
	ds_read2st64_b32 v[12:13], v9 offset0:96 offset1:97
	ds_read2st64_b32 v[14:15], v9 offset0:34 offset1:35
	ds_read2st64_b32 v[48:49], v9 offset0:98 offset1:99
	s_waitcnt lgkmcnt(2)
	v_fma_f32 v12, 0, v10, v12
	v_fmac_f32_e32 v13, v12, v11
	v_mul_f32_e32 v10, v10, v11
	s_waitcnt lgkmcnt(0)
	v_fma_f32 v11, v13, v14, v48
	ds_read2st64_b32 v[12:13], v9 offset0:36 offset1:37
	ds_read2st64_b32 v[50:51], v9 offset0:100 offset1:101
	v_fmac_f32_e32 v49, v11, v15
	v_mov_b32_e32 v58, v14
	v_mul_f32_e32 v14, v10, v14
	v_mul_f32_e32 v14, v14, v15
	s_waitcnt lgkmcnt(0)
	v_fma_f32 v11, v49, v12, v50
	ds_read2st64_b32 v[48:49], v9 offset0:38 offset1:39
	ds_read2st64_b32 v[52:53], v9 offset0:102 offset1:103
	v_fmac_f32_e32 v51, v11, v13
	s_waitcnt lgkmcnt(1)
	v_mov_b32_e32 v62, v48
	s_waitcnt lgkmcnt(0)
	v_fma_f32 v11, v51, v48, v52
	ds_read2st64_b32 v[50:51], v9 offset0:40 offset1:41
	ds_read2st64_b32 v[54:55], v9 offset0:104 offset1:105
	v_fmac_f32_e32 v53, v11, v49
	s_waitcnt lgkmcnt(1)
	v_mov_b32_e32 v59, v51
	s_waitcnt lgkmcnt(0)
	v_fmac_f32_e32 v54, v53, v50
	ds_read2st64_b32 v[52:53], v9 offset0:42 offset1:43
	ds_read2st64_b32 v[56:57], v9 offset0:106 offset1:107
	v_mov_b32_e32 v11, v54
	v_mov_b32_e32 v54, v15
	v_pk_fma_f32 v[10:11], v[10:11], v[58:59], v[54:55]
	v_mov_b32_e32 v58, v13
	v_mov_b32_e32 v15, v11
	v_mov_b32_e32 v10, v12
	s_waitcnt lgkmcnt(1)
	v_mov_b32_e32 v11, v52
	v_pk_mul_f32 v[54:55], v[14:15], v[10:11]
	v_mov_b32_e32 v12, v13
	s_waitcnt lgkmcnt(0)
	v_mov_b32_e32 v59, v56
	v_pk_mul_f32 v[12:13], v[54:55], v[12:13]
	v_pk_fma_f32 v[10:11], v[14:15], v[10:11], v[58:59]
	ds_read2st64_b32 v[14:15], v9 offset0:44 offset1:45
	ds_read2st64_b32 v[54:55], v9 offset0:108 offset1:109
	ds_read2st64_b32 v[58:59], v9 offset0:46 offset1:47
	ds_read2st64_b32 v[60:61], v9 offset0:110 offset1:111
	v_and_b32_e32 v56, 0x1fffffc0, v83
	v_lshl_add_u32 v9, v8, 3, s60
	v_mov_b32_e32 v10, v12
	v_lshl_add_u32 v64, v56, 3, v9
	v_mov_b32_e32 v63, v53
	v_pk_mul_f32 v[12:13], v[12:13], v[48:49]
	v_mov_b32_e32 v48, v49
	v_mov_b32_e32 v56, v49
	v_pk_mul_f32 v[12:13], v[12:13], v[48:49]
	v_pk_fma_f32 v[10:11], v[10:11], v[62:63], v[56:57]
	v_mov_b32_e32 v56, v51
	v_mov_b32_e32 v13, v11
	v_mov_b32_e32 v10, v50
	s_waitcnt lgkmcnt(3)
	v_mov_b32_e32 v11, v14
	v_pk_mul_f32 v[48:49], v[12:13], v[10:11]
	v_mov_b32_e32 v50, v51
	s_waitcnt lgkmcnt(2)
	v_mov_b32_e32 v57, v54
	v_pk_mul_f32 v[48:49], v[48:49], v[50:51]
	v_pk_fma_f32 v[10:11], v[12:13], v[10:11], v[56:57]
	v_mov_b32_e32 v12, v52
	v_mov_b32_e32 v10, v48
	v_mov_b32_e32 v13, v15
	v_pk_mul_f32 v[48:49], v[48:49], v[52:53]
	v_mov_b32_e32 v50, v53
	v_mov_b32_e32 v54, v53
	v_pk_mul_f32 v[48:49], v[48:49], v[50:51]
	v_pk_fma_f32 v[10:11], v[10:11], v[12:13], v[54:55]
	v_mov_b32_e32 v50, v15
	v_mov_b32_e32 v49, v11
	v_mov_b32_e32 v10, v14
	s_waitcnt lgkmcnt(1)
	v_mov_b32_e32 v11, v58
	v_pk_mul_f32 v[12:13], v[48:49], v[10:11]
	v_mov_b32_e32 v14, v15
	s_waitcnt lgkmcnt(0)
	v_mov_b32_e32 v51, v60
	v_pk_mul_f32 v[12:13], v[12:13], v[14:15]
	v_pk_fma_f32 v[10:11], v[48:49], v[10:11], v[50:51]
	v_mov_b32_e32 v14, v59
	v_mov_b32_e32 v10, v12
	v_pk_mul_f32 v[12:13], v[12:13], v[58:59]
	v_mov_b32_e32 v60, v59
	v_pk_mul_f32 v[12:13], v[12:13], v[14:15]
	v_pk_fma_f32 v[10:11], v[10:11], v[58:59], v[60:61]
	s_nop 0
	v_mov_b32_e32 v13, v11
	ds_write_b64 v64, v[12:13] offset:40960
	s_waitcnt lgkmcnt(0)
	s_barrier
	s_and_saveexec_b64 s[6:7], vcc
	s_xor_b64 s[6:7], exec, s[6:7]
	s_cbranch_execz .LBB0_401
	s_lshl_b32 s27, s26, 7
	ds_read2st64_b64 v[10:13], v9 offset0:80 offset1:81
	ds_read2st64_b64 v[48:51], v9 offset0:82 offset1:83
	s_or_b32 s28, s27, s25
	s_ashr_i32 s29, s28, 31
	s_lshl_b64 s[28:29], s[28:29], 12
	s_mov_b64 s[30:31], s[74:75]
	s_add_u32 s27, s30, s28
	s_waitcnt lgkmcnt(1)
	v_fma_f32 v9, 0, v10, v11
	s_addc_u32 s29, s31, s29
	s_lshl_b32 s28, s23, 3
	v_fmac_f32_e32 v13, v9, v12
	s_add_u32 s28, s27, s28
	v_mul_f32_e32 v10, v10, v12
	s_waitcnt lgkmcnt(0)
	v_fma_f32 v11, v13, v48, v49
	v_mov_b32_e32 v49, v50
	s_addc_u32 s29, s29, 0
	v_lshlrev_b32_e32 v144, 3, v8
	v_pk_mul_f32 v[12:13], v[10:11], v[48:49]
	v_lshl_add_u64 v[8:9], s[28:29], 0, v[144:145]
	v_pk_mul_f32 v[12:13], v[12:13], v[50:51]
	v_pk_fma_f32 v[10:11], v[10:11], v[48:49], v[50:51]
	v_add_co_u32_e32 v8, vcc, 0x115e0000, v8
	v_mov_b32_e32 v13, v11
	s_nop 0
	v_addc_co_u32_e32 v9, vcc, 0, v9, vcc
	flat_store_dwordx2 v[8:9], v[12:13]
.LBB0_401:
	s_or_b64 exec, exec, s[6:7]
	v_mov_b32_e32 v75, v191
	s_waitcnt lgkmcnt(0)
	s_barrier
	v_mov_b32_e32 v74, v191
	v_and_b32_e32 v83, 15, v75
	v_lshrrev_b32_e32 v96, 4, v75
	v_bfe_u32 v97, v75, 4, 2
	s_mov_b64 s[6:7], s[74:75]
	v_bfe_u32 v77, v75, 1, 3
	v_ashrrev_i32_e32 v76, 6, v75
	v_lshlrev_b32_e32 v72, 7, v83
	v_bitop3_b32 v8, v96, v77, 3 bitop3:0x6c
	v_bitop3_b32 v13, v97, v77, 4 bitop3:0x36
	v_lshl_or_b32 v12, v76, 11, v72
	v_lshlrev_b32_e32 v8, 4, v8
	v_lshlrev_b32_e32 v13, 4, v13
	s_add_u32 s6, s6, s24
	v_add3_u32 v8, s60, v8, v12
	v_add3_u32 v12, s60, v13, v12
	s_addc_u32 s7, s7, 0
	v_lshlrev_b32_e32 v144, 4, v97
	ds_read_b128 v[8:11], v8
	ds_read_b128 v[84:87], v12
	v_lshl_add_u64 v[12:13], s[6:7], 0, v[144:145]
	s_mov_b64 s[6:7], 0x3980000
	v_lshl_add_u64 v[92:93], v[12:13], 0, s[6:7]
	s_mov_b64 s[6:7], 0x39a0000
	v_mov_b32_e32 v73, v145
	v_lshl_add_u64 v[94:95], v[12:13], 0, s[6:7]
	v_lshl_add_u64 v[60:61], v[92:93], 0, v[72:73]
	v_lshl_add_u64 v[62:63], v[94:95], 0, v[72:73]
	s_mov_b64 s[98:99], 0x1000
	v_lshl_add_u64 v[180:181], v[60:61], 0, s[98:99]
	v_lshl_add_u64 v[182:183], v[62:63], 0, s[98:99]
	global_load_dwordx4 v[104:107], v[180:181], off offset:-4096
	global_load_dwordx4 v[108:111], v[182:183], off offset:-4096
	global_load_dwordx4 v[112:115], v[180:181], off offset:-4032
	global_load_dwordx4 v[116:119], v[182:183], off offset:-4032
	global_load_dwordx4 v[120:123], v[180:181], off offset:-2048
	global_load_dwordx4 v[124:127], v[182:183], off offset:-2048
	global_load_dwordx4 v[128:131], v[180:181], off offset:-1984
	global_load_dwordx4 v[132:135], v[182:183], off offset:-1984
	global_load_dwordx4 v[136:139], v[180:181], off
	global_load_dwordx4 v[140:143], v[182:183], off
	global_load_dwordx4 v[156:159], v[180:181], off offset:64
	global_load_dwordx4 v[160:163], v[182:183], off offset:64
	global_load_dwordx4 v[164:167], v[180:181], off offset:2048
	global_load_dwordx4 v[168:171], v[182:183], off offset:2048
	global_load_dwordx4 v[172:175], v[180:181], off offset:2112
	global_load_dwordx4 v[176:179], v[182:183], off offset:2112
	v_readlane_b32 s36, v254, 22
	v_readlane_b32 s40, v254, 26
	v_readlane_b32 s41, v254, 27
	s_mov_b64 s[6:7], s[40:41]
	v_readlane_b32 s44, v254, 30
	v_readlane_b32 s45, v254, 31
	s_mov_b32 s27, 0x122e6000
	s_mov_b32 s28, 0xc1000000
	v_lshrrev_b32_e32 v98, 1, v75
	v_readlane_b32 s37, v254, 23
	v_readlane_b32 s38, v254, 24
	v_readlane_b32 s39, v254, 25
	v_readlane_b32 s42, v254, 28
	v_readlane_b32 s43, v254, 29
	v_readlane_b32 s46, v254, 32
	v_readlane_b32 s47, v254, 33
	v_readlane_b32 s48, v254, 34
	v_readlane_b32 s49, v254, 35
	v_readlane_b32 s50, v254, 36
	v_readlane_b32 s51, v254, 37
	v_lshlrev_b32_e32 v154, 2, v97
	v_or_b32_e32 v154, s8, v154
	v_ashrrev_i32_e32 v155, 31, v154
	v_lshlrev_b64 v[154:155], 2, v[154:155]
	s_add_u32 s98, s74, s3
	s_addc_u32 s99, s75, 0
	s_add_u32 s98, s98, 0x122e6000
	s_addc_u32 s99, s99, 0
	v_lshl_add_u64 v[184:185], s[98:99], 0, v[144:145]
	v_lshl_add_u64 v[180:181], s[40:41], 0, v[154:155]
	v_lshl_add_u64 v[146:147], s[44:45], 0, v[154:155]
	global_load_dwordx4 v[216:219], v[180:181], off offset:2048
	global_load_dwordx4 v[220:223], v[146:147], off offset:2048
	global_load_dwordx4 v[224:227], v[184:185], off offset:2048
	global_load_dwordx4 v[228:231], v[180:181], off offset:2112
	global_load_dwordx4 v[232:235], v[146:147], off offset:2112
	global_load_dwordx4 v[236:239], v[184:185], off offset:2112
	global_load_dwordx4 v[240:243], v[180:181], off offset:2176
	global_load_dwordx4 v[244:247], v[146:147], off offset:2176
	global_load_dwordx4 v[248:251], v[184:185], off offset:2176
	global_load_dwordx4 v[180:183], v[180:181], off offset:2240
	global_load_dwordx4 v[146:149], v[146:147], off offset:2240
	s_waitcnt vmcnt(0) lgkmcnt(0)
	v_mfma_f32_16x16x32_bf16 v[12:15], v[104:107], v[8:11], 0
	v_mfma_f32_16x16x32_bf16 v[48:51], v[108:111], v[8:11], 0
	v_mfma_f32_16x16x32_bf16 v[68:71], v[112:115], v[84:87], v[12:15]
	v_mfma_f32_16x16x32_bf16 v[64:67], v[116:119], v[84:87], v[48:51]
	s_nop 4
	v_mfma_f32_16x16x32_bf16 v[12:15], v[120:123], v[8:11], 0
	v_mfma_f32_16x16x32_bf16 v[48:51], v[124:127], v[8:11], 0
	v_mfma_f32_16x16x32_bf16 v[60:63], v[128:131], v[84:87], v[12:15]
	s_nop 5
	v_or_b32_e32 v12, 0x1000, v72
	v_mov_b32_e32 v13, v145
	v_lshl_add_u64 v[52:53], v[92:93], 0, v[12:13]
	v_mfma_f32_16x16x32_bf16 v[56:59], v[132:135], v[84:87], v[48:51]
	v_lshl_add_u64 v[88:89], v[94:95], 0, v[12:13]
	s_nop 0
	s_nop 0
	s_nop 0
	v_mfma_f32_16x16x32_bf16 v[12:15], v[136:139], v[8:11], 0
	v_mfma_f32_16x16x32_bf16 v[48:51], v[140:143], v[8:11], 0
	v_mfma_f32_16x16x32_bf16 v[52:55], v[156:159], v[84:87], v[12:15]
	s_nop 5
	v_or_b32_e32 v12, 0x1800, v72
	v_mov_b32_e32 v13, v145
	v_lshl_add_u64 v[72:73], v[92:93], 0, v[12:13]
	v_mfma_f32_16x16x32_bf16 v[48:51], v[160:163], v[84:87], v[48:51]
	v_lshl_add_u64 v[92:93], v[94:95], 0, v[12:13]
	v_mfma_f32_16x16x32_bf16 v[12:15], v[164:167], v[8:11], 0
	v_mfma_f32_16x16x32_bf16 v[8:11], v[168:171], v[8:11], 0
	s_nop 0
	v_lshl_or_b32 v73, v76, 4, v83
	v_lshlrev_b32_e32 v72, 2, v97
	v_lshlrev_b32_e32 v83, 7, v73
	v_lshlrev_b32_e32 v102, 8, v73
	v_mov_b32_e32 v73, v145
	v_mfma_f32_16x16x32_bf16 v[12:15], v[172:175], v[84:87], v[12:15]
	v_mfma_f32_16x16x32_bf16 v[8:11], v[176:179], v[84:87], v[8:11]
	global_load_dwordx4 v[104:107], v[184:185], off offset:2240
	v_lshl_add_u64 v[86:87], v[72:73], 0, s[8:9]
	v_lshlrev_b64 v[90:91], 2, v[86:87]
	v_lshl_add_u64 v[86:87], s[6:7], 0, v[90:91]
	s_mov_b64 s[6:7], s[44:45]
	v_bfe_u32 v84, v96, 1, 1
	v_lshl_add_u64 v[90:91], s[6:7], 0, v[90:91]
	s_mov_b64 s[6:7], s[74:75]
	s_add_u32 s6, s6, s3
	s_addc_u32 s7, s7, 0
	v_lshl_add_u64 v[94:95], s[6:7], 0, v[144:145]
	v_add_co_u32_e32 v94, vcc, s27, v94
	v_and_b32_e32 v85, 8, v98
	s_nop 0
	v_addc_co_u32_e32 v95, vcc, 0, v95, vcc
	v_bitop3_b32 v98, v84, v98, 7 bitop3:0x78
	v_add_u32_e32 v85, s60, v85
	v_lshlrev_b32_e32 v98, 4, v98
	v_add3_u32 v98, v85, v98, v83
	ds_read_b64 v[98:99], v98
	s_waitcnt lgkmcnt(0)
	v_lshlrev_b32_e32 v100, 16, v98
	v_and_b32_e32 v101, 0xffff0000, v98
	v_lshlrev_b32_e32 v98, 16, v99
	v_and_b32_e32 v99, 0xffff0000, v99
	v_add_f32_e32 v68, v68, v216
	v_add_f32_e32 v69, v69, v217
	v_mul_f32_e32 v68, 0xbfb8aa3b, v68
	v_mul_f32_e32 v69, 0xbfb8aa3b, v69
	v_exp_f32_e32 v68, v68
	v_exp_f32_e32 v69, v69
	v_add_f32_e32 v64, v64, v220
	v_add_f32_e32 v65, v65, v221
	v_add_f32_e32 v68, 1.0, v68
	v_add_f32_e32 v69, 1.0, v69
	v_rcp_f32_e32 v68, v68
	v_rcp_f32_e32 v69, v69
	v_add_f32_e32 v70, v70, v218
	v_add_f32_e32 v71, v71, v219
	v_mul_f32_e32 v70, 0xbfb8aa3b, v70
	v_pk_mul_f32 v[68:69], v[68:69], s[28:29] op_sel_hi:[1,0]
	v_mul_f32_e32 v71, 0xbfb8aa3b, v71
	v_pk_mul_f32 v[86:87], v[224:225], v[68:69]
	v_exp_f32_e32 v70, v70
	v_pk_add_f32 v[90:91], v[86:87], v[86:87]
	v_mul_f32_e32 v68, 0x3fb8aa3b, v86
	v_fmamk_f32 v69, v90, 0x3ab60b61, v195
	v_exp_f32_e32 v68, v68
	v_fmaak_f32 v69, v90, v69, 0x3d2aaaab
	v_fmaak_f32 v69, v90, v69, 0x3e2aaaab
	v_exp_f32_e32 v71, v71
	v_fma_f32 v69, v90, v69, 0.5
	v_fma_f32 v69, v90, v69, 1.0
	v_mul_f32_e64 v69, v69, -v90
	v_fma_f32 v86, -v68, v68, 1.0
	v_cmp_lt_f32_e64 s[6:7], s84, v90
	v_add_f32_e32 v70, 1.0, v70
	v_add_f32_e32 v71, 1.0, v71
	v_cndmask_b32_e64 v69, v86, v69, s[6:7]
	v_sqrt_f32_e32 v86, v69
	v_mul_f32_e32 v69, 0x3fb8aa3b, v87
	v_fmamk_f32 v87, v91, 0x3ab60b61, v195
	v_rcp_f32_e32 v70, v70
	v_rcp_f32_e32 v71, v71
	v_exp_f32_e32 v69, v69
	v_fmaak_f32 v87, v91, v87, 0x3d2aaaab
	v_fmaak_f32 v87, v91, v87, 0x3e2aaaab
	v_fma_f32 v87, v91, v87, 0.5
	v_fma_f32 v87, v91, v87, 1.0
	v_pk_mul_f32 v[70:71], v[70:71], s[28:29] op_sel_hi:[1,0]
	v_cmp_lt_f32_e32 vcc, s84, v91
	v_mul_f32_e64 v87, v87, -v91
	v_fma_f32 v90, -v69, v69, 1.0
	v_pk_mul_f32 v[88:89], v[226:227], v[70:71]
	v_cndmask_b32_e32 v87, v90, v87, vcc
	v_pk_add_f32 v[90:91], v[88:89], v[88:89]
	v_mul_f32_e32 v70, 0x3fb8aa3b, v88
	v_fmamk_f32 v71, v90, 0x3ab60b61, v195
	v_exp_f32_e32 v70, v70
	v_fmaak_f32 v71, v90, v71, 0x3d2aaaab
	v_fmaak_f32 v71, v90, v71, 0x3e2aaaab
	v_fma_f32 v71, v90, v71, 0.5
	v_fma_f32 v71, v90, v71, 1.0
	v_mul_f32_e64 v71, v71, -v90
	v_fma_f32 v88, -v70, v70, 1.0
	v_cmp_lt_f32_e64 s[6:7], s84, v90
	v_add_f32_e32 v66, v66, v222
	v_add_f32_e32 v67, v67, v223
	v_cndmask_b32_e64 v71, v88, v71, s[6:7]
	v_sqrt_f32_e32 v88, v71
	v_mul_f32_e32 v71, 0x3fb8aa3b, v89
	v_fmamk_f32 v89, v91, 0x3ab60b61, v195
	v_mul_f32_e32 v64, 0xbfb8aa3b, v64
	v_mul_f32_e32 v65, 0xbfb8aa3b, v65
	v_mul_f32_e32 v66, 0xbfb8aa3b, v66
	v_mul_f32_e32 v67, 0xbfb8aa3b, v67
	v_exp_f32_e32 v71, v71
	v_fmaak_f32 v89, v91, v89, 0x3d2aaaab
	v_exp_f32_e32 v64, v64
	v_exp_f32_e32 v65, v65
	v_exp_f32_e32 v66, v66
	v_exp_f32_e32 v67, v67
	v_fmaak_f32 v89, v91, v89, 0x3e2aaaab
	v_fma_f32 v89, v91, v89, 0.5
	v_fma_f32 v89, v91, v89, 1.0
	v_cmp_lt_f32_e32 vcc, s84, v91
	v_mul_f32_e64 v89, v89, -v91
	v_fma_f32 v90, -v71, v71, 1.0
	v_add_f32_e32 v64, 1.0, v64
	v_add_f32_e32 v65, 1.0, v65
	v_add_f32_e32 v66, 1.0, v66
	v_add_f32_e32 v67, 1.0, v67
	v_cndmask_b32_e32 v89, v90, v89, vcc
	v_rcp_f32_e32 v64, v64
	v_rcp_f32_e32 v65, v65
	v_sqrt_f32_e32 v87, v87
	v_rcp_f32_e32 v66, v66
	v_rcp_f32_e32 v67, v67
	v_sqrt_f32_e32 v89, v89
	v_pk_mul_f32 v[64:65], v[64:65], v[86:87]
	s_mov_b64 s[6:7], s[40:41]
	v_pk_mul_f32 v[86:87], v[64:65], v[100:101]
	v_pk_mul_f32 v[66:67], v[66:67], v[88:89]
	v_lshl_add_u64 v[64:65], v[72:73], 0, s[12:13]
	v_pk_mul_f32 v[88:89], v[66:67], v[98:99]
	v_add3_u32 v66, s60, v102, v144
	ds_write_b128 v66, v[68:71] offset:8192
	ds_write_b128 v66, v[86:89] offset:24576
	v_lshlrev_b64 v[64:65], 2, v[64:65]
	v_lshl_add_u64 v[68:69], s[6:7], 0, v[64:65]
	s_mov_b64 s[6:7], s[44:45]
	v_bitop3_b32 v67, v84, v77, 2 bitop3:0x36
	v_lshl_add_u64 v[72:73], s[6:7], 0, v[64:65]
	s_mov_b64 s[6:7], s[74:75]
	s_add_u32 s6, s6, s3
	s_addc_u32 s7, s7, 0
	v_lshl_add_u64 v[72:73], s[6:7], 0, v[144:145]
	v_add_co_u32_e32 v72, vcc, s27, v72
	v_lshlrev_b32_e32 v67, 4, v67
	s_nop 0
	v_addc_co_u32_e32 v73, vcc, 0, v73, vcc
	v_add3_u32 v67, v85, v67, v83
	ds_read_b64 v[72:73], v67
	s_waitcnt lgkmcnt(0)
	v_lshlrev_b32_e32 v94, 16, v72
	v_and_b32_e32 v95, 0xffff0000, v72
	v_lshlrev_b32_e32 v72, 16, v73
	v_and_b32_e32 v73, 0xffff0000, v73
	v_add_f32_e32 v60, v60, v228
	v_mul_f32_e32 v60, 0xbfb8aa3b, v60
	v_exp_f32_e32 v60, v60
	v_add_f32_e32 v62, v62, v230
	v_add_f32_e32 v56, v56, v232
	v_mul_f32_e32 v56, 0xbfb8aa3b, v56
	v_exp_f32_e32 v56, v56
	v_add_f32_e32 v58, v58, v234
	v_mul_f32_e32 v58, 0xbfb8aa3b, v58
	v_exp_f32_e32 v58, v58
	v_add_f32_e32 v56, 1.0, v56
	v_rcp_f32_e32 v68, v56
	v_add_f32_e32 v56, v61, v229
	v_mul_f32_e32 v56, 0xbfb8aa3b, v56
	v_exp_f32_e32 v56, v56
	v_add_f32_e32 v60, 1.0, v60
	v_rcp_f32_e32 v60, v60
	v_add_f32_e32 v58, 1.0, v58
	v_add_f32_e32 v56, 1.0, v56
	v_rcp_f32_e32 v61, v56
	v_add_f32_e32 v56, v57, v233
	v_mul_f32_e32 v56, 0xbfb8aa3b, v56
	v_exp_f32_e32 v56, v56
	v_rcp_f32_e32 v70, v58
	v_add_f32_e32 v58, v63, v231
	v_mul_f32_e32 v58, 0xbfb8aa3b, v58
	v_add_f32_e32 v56, 1.0, v56
	v_rcp_f32_e32 v69, v56
	v_pk_mul_f32 v[56:57], v[60:61], s[28:29] op_sel_hi:[1,0]
	v_exp_f32_e32 v58, v58
	v_pk_mul_f32 v[60:61], v[236:237], v[56:57]
	v_mul_f32_e32 v62, 0xbfb8aa3b, v62
	v_pk_add_f32 v[86:87], v[60:61], v[60:61]
	v_mul_f32_e32 v56, 0x3fb8aa3b, v60
	v_fmamk_f32 v57, v86, 0x3ab60b61, v195
	v_exp_f32_e32 v56, v56
	v_fmaak_f32 v57, v86, v57, 0x3d2aaaab
	v_exp_f32_e32 v62, v62
	v_fmaak_f32 v57, v86, v57, 0x3e2aaaab
	v_add_f32_e32 v58, 1.0, v58
	v_fma_f32 v57, v86, v57, 0.5
	v_rcp_f32_e32 v63, v58
	v_add_f32_e32 v58, v59, v235
	v_fma_f32 v57, v86, v57, 1.0
	v_mul_f32_e32 v58, 0xbfb8aa3b, v58
	v_mul_f32_e64 v57, v57, -v86
	v_fma_f32 v60, -v56, v56, 1.0
	v_cmp_lt_f32_e64 s[6:7], s84, v86
	v_add_f32_e32 v62, 1.0, v62
	v_exp_f32_e32 v58, v58
	v_cndmask_b32_e64 v57, v60, v57, s[6:7]
	v_rcp_f32_e32 v62, v62
	v_sqrt_f32_e32 v60, v57
	v_mul_f32_e32 v57, 0x3fb8aa3b, v61
	v_fmamk_f32 v61, v87, 0x3ab60b61, v195
	v_fmaak_f32 v61, v87, v61, 0x3d2aaaab
	v_fmaak_f32 v61, v87, v61, 0x3e2aaaab
	v_add_f32_e32 v58, 1.0, v58
	v_fma_f32 v61, v87, v61, 0.5
	v_rcp_f32_e32 v71, v58
	v_pk_mul_f32 v[58:59], v[62:63], s[28:29] op_sel_hi:[1,0]
	v_fma_f32 v61, v87, v61, 1.0
	v_pk_mul_f32 v[62:63], v[238:239], v[58:59]
	v_cmp_lt_f32_e32 vcc, s84, v87
	v_mul_f32_e64 v61, v61, -v87
	v_pk_add_f32 v[86:87], v[62:63], v[62:63]
	v_mul_f32_e32 v58, 0x3fb8aa3b, v62
	v_fmamk_f32 v59, v86, 0x3ab60b61, v195
	v_exp_f32_e32 v58, v58
	v_fmaak_f32 v59, v86, v59, 0x3d2aaaab
	v_fmaak_f32 v59, v86, v59, 0x3e2aaaab
	v_fma_f32 v59, v86, v59, 0.5
	v_fma_f32 v59, v86, v59, 1.0
	v_mul_f32_e64 v59, v59, -v86
	v_fma_f32 v62, -v58, v58, 1.0
	v_cmp_lt_f32_e64 s[6:7], s84, v86
	v_exp_f32_e32 v57, v57
	s_nop 0
	v_cndmask_b32_e64 v59, v62, v59, s[6:7]
	v_sqrt_f32_e32 v62, v59
	v_mul_f32_e32 v59, 0x3fb8aa3b, v63
	v_fmamk_f32 v63, v87, 0x3ab60b61, v195
	v_exp_f32_e32 v59, v59
	v_fmaak_f32 v63, v87, v63, 0x3d2aaaab
	v_fmaak_f32 v63, v87, v63, 0x3e2aaaab
	v_fma_f32 v63, v87, v63, 0.5
	v_fma_f32 v67, -v57, v57, 1.0
	v_fma_f32 v63, v87, v63, 1.0
	v_cndmask_b32_e32 v61, v67, v61, vcc
	v_cmp_lt_f32_e32 vcc, s84, v87
	v_mul_f32_e64 v63, v63, -v87
	v_fma_f32 v67, -v59, v59, 1.0
	v_cndmask_b32_e32 v63, v67, v63, vcc
	v_sqrt_f32_e32 v61, v61
	v_sqrt_f32_e32 v63, v63
	s_mov_b64 s[6:7], s[40:41]
	v_bitop3_b32 v67, v84, v77, 4 bitop3:0x36
	v_pk_mul_f32 v[60:61], v[68:69], v[60:61]
	v_pk_mul_f32 v[62:63], v[70:71], v[62:63]
	v_pk_mul_f32 v[60:61], v[60:61], v[94:95]
	v_pk_mul_f32 v[62:63], v[62:63], v[72:73]
	ds_write_b128 v66, v[56:59] offset:8256
	ds_write_b128 v66, v[60:63] offset:24640
	v_lshlrev_b32_e32 v67, 4, v67
	v_lshl_add_u64 v[56:57], s[6:7], 0, v[64:65]
	s_mov_b64 s[6:7], s[44:45]
	v_add3_u32 v67, v85, v67, v83
	v_lshl_add_u64 v[60:61], s[6:7], 0, v[64:65]
	s_mov_b64 s[6:7], s[74:75]
	s_add_u32 s6, s6, s3
	s_addc_u32 s7, s7, 0
	v_lshl_add_u64 v[68:69], s[6:7], 0, v[144:145]
	v_add_co_u32_e32 v68, vcc, s27, v68
	ds_read_b64 v[72:73], v67
	s_nop 0
	v_addc_co_u32_e32 v69, vcc, 0, v69, vcc
	s_waitcnt lgkmcnt(0)
	v_lshlrev_b32_e32 v86, 16, v72
	v_and_b32_e32 v87, 0xffff0000, v72
	v_lshlrev_b32_e32 v72, 16, v73
	v_and_b32_e32 v73, 0xffff0000, v73
	v_add_f32_e32 v52, v52, v240
	v_mul_f32_e32 v52, 0xbfb8aa3b, v52
	v_exp_f32_e32 v52, v52
	v_add_f32_e32 v54, v54, v242
	v_add_f32_e32 v48, v48, v244
	v_mul_f32_e32 v48, 0xbfb8aa3b, v48
	v_exp_f32_e32 v48, v48
	v_add_f32_e32 v50, v50, v246
	v_mul_f32_e32 v50, 0xbfb8aa3b, v50
	v_add_f32_e32 v52, 1.0, v52
	v_add_f32_e32 v48, 1.0, v48
	v_rcp_f32_e32 v56, v48
	v_add_f32_e32 v48, v53, v241
	v_mul_f32_e32 v48, 0xbfb8aa3b, v48
	v_exp_f32_e32 v48, v48
	v_exp_f32_e32 v50, v50
	v_rcp_f32_e32 v52, v52
	v_mul_f32_e32 v54, 0xbfb8aa3b, v54
	v_add_f32_e32 v48, 1.0, v48
	v_rcp_f32_e32 v53, v48
	v_add_f32_e32 v48, v49, v245
	v_mul_f32_e32 v48, 0xbfb8aa3b, v48
	v_exp_f32_e32 v48, v48
	v_add_f32_e32 v50, 1.0, v50
	v_rcp_f32_e32 v58, v50
	v_add_f32_e32 v50, v55, v243
	v_add_f32_e32 v48, 1.0, v48
	v_rcp_f32_e32 v57, v48
	v_pk_mul_f32 v[48:49], v[52:53], s[28:29] op_sel_hi:[1,0]
	v_mul_f32_e32 v50, 0xbfb8aa3b, v50
	v_pk_mul_f32 v[52:53], v[248:249], v[48:49]
	v_exp_f32_e32 v50, v50
	v_pk_add_f32 v[60:61], v[52:53], v[52:53]
	v_mul_f32_e32 v48, 0x3fb8aa3b, v52
	v_fmamk_f32 v49, v60, 0x3ab60b61, v195
	v_exp_f32_e32 v48, v48
	v_fmaak_f32 v49, v60, v49, 0x3d2aaaab
	v_fmaak_f32 v49, v60, v49, 0x3e2aaaab
	v_exp_f32_e32 v54, v54
	v_fma_f32 v49, v60, v49, 0.5
	v_add_f32_e32 v50, 1.0, v50
	v_fma_f32 v49, v60, v49, 1.0
	v_rcp_f32_e32 v55, v50
	v_add_f32_e32 v50, v51, v247
	v_mul_f32_e64 v49, v49, -v60
	v_fma_f32 v52, -v48, v48, 1.0
	v_cmp_lt_f32_e64 s[6:7], s84, v60
	v_mul_f32_e32 v50, 0xbfb8aa3b, v50
	v_add_f32_e32 v54, 1.0, v54
	v_cndmask_b32_e64 v49, v52, v49, s[6:7]
	v_exp_f32_e32 v50, v50
	v_sqrt_f32_e32 v52, v49
	v_mul_f32_e32 v49, 0x3fb8aa3b, v53
	v_fmamk_f32 v53, v61, 0x3ab60b61, v195
	v_rcp_f32_e32 v54, v54
	v_exp_f32_e32 v49, v49
	v_fmaak_f32 v53, v61, v53, 0x3d2aaaab
	v_fmaak_f32 v53, v61, v53, 0x3e2aaaab
	v_fma_f32 v53, v61, v53, 0.5
	v_add_f32_e32 v50, 1.0, v50
	v_fma_f32 v53, v61, v53, 1.0
	v_rcp_f32_e32 v59, v50
	v_pk_mul_f32 v[50:51], v[54:55], s[28:29] op_sel_hi:[1,0]
	v_cmp_lt_f32_e32 vcc, s84, v61
	v_mul_f32_e64 v53, v53, -v61
	v_fma_f32 v60, -v49, v49, 1.0
	v_pk_mul_f32 v[54:55], v[250:251], v[50:51]
	v_cndmask_b32_e32 v53, v60, v53, vcc
	v_pk_add_f32 v[60:61], v[54:55], v[54:55]
	v_mul_f32_e32 v50, 0x3fb8aa3b, v54
	v_fmamk_f32 v51, v60, 0x3ab60b61, v195
	v_exp_f32_e32 v50, v50
	v_fmaak_f32 v51, v60, v51, 0x3d2aaaab
	v_fmaak_f32 v51, v60, v51, 0x3e2aaaab
	v_fma_f32 v51, v60, v51, 0.5
	v_fma_f32 v51, v60, v51, 1.0
	v_mul_f32_e64 v51, v51, -v60
	v_fma_f32 v54, -v50, v50, 1.0
	v_cmp_lt_f32_e64 s[6:7], s84, v60
	v_cmp_lt_f32_e32 vcc, s84, v61
	v_sqrt_f32_e32 v53, v53
	v_cndmask_b32_e64 v51, v54, v51, s[6:7]
	v_sqrt_f32_e32 v54, v51
	v_mul_f32_e32 v51, 0x3fb8aa3b, v55
	v_fmamk_f32 v55, v61, 0x3ab60b61, v195
	v_exp_f32_e32 v51, v51
	v_fmaak_f32 v55, v61, v55, 0x3d2aaaab
	v_fmaak_f32 v55, v61, v55, 0x3e2aaaab
	v_fma_f32 v55, v61, v55, 0.5
	v_fma_f32 v55, v61, v55, 1.0
	v_mul_f32_e64 v55, v55, -v61
	v_fma_f32 v60, -v51, v51, 1.0
	v_cndmask_b32_e32 v55, v60, v55, vcc
	v_sqrt_f32_e32 v55, v55
	v_pk_mul_f32 v[52:53], v[56:57], v[52:53]
	s_mov_b64 s[6:7], s[40:41]
	v_pk_mul_f32 v[52:53], v[52:53], v[86:87]
	v_pk_mul_f32 v[54:55], v[58:59], v[54:55]
	v_bitop3_b32 v60, v84, v77, 6 bitop3:0x36
	v_pk_mul_f32 v[54:55], v[54:55], v[72:73]
	ds_write_b128 v66, v[48:51] offset:8320
	ds_write_b128 v66, v[52:55] offset:24704
	v_lshlrev_b32_e32 v60, 4, v60
	v_lshl_add_u64 v[48:49], s[6:7], 0, v[64:65]
	s_mov_b64 s[6:7], s[44:45]
	v_add3_u32 v60, v85, v60, v83
	v_lshl_add_u64 v[52:53], s[6:7], 0, v[64:65]
	s_mov_b64 s[6:7], s[74:75]
	s_add_u32 s6, s6, s3
	s_addc_u32 s7, s7, 0
	v_lshl_add_u64 v[56:57], s[6:7], 0, v[144:145]
	v_add_co_u32_e32 v56, vcc, s27, v56
	ds_read_b64 v[60:61], v60
	s_nop 0
	v_addc_co_u32_e32 v57, vcc, 0, v57, vcc
	s_waitcnt lgkmcnt(0)
	v_lshlrev_b32_e32 v62, 16, v60
	v_and_b32_e32 v63, 0xffff0000, v60
	v_lshlrev_b32_e32 v60, 16, v61
	v_and_b32_e32 v61, 0xffff0000, v61
	s_waitcnt vmcnt(0)
	v_add_f32_e32 v12, v12, v180
	v_mul_f32_e32 v12, 0xbfb8aa3b, v12
	v_exp_f32_e32 v12, v12
	v_add_f32_e32 v14, v14, v182
	v_add_f32_e32 v8, v8, v146
	v_mul_f32_e32 v8, 0xbfb8aa3b, v8
	v_exp_f32_e32 v8, v8
	v_add_f32_e32 v10, v10, v148
	v_mul_f32_e32 v10, 0xbfb8aa3b, v10
	v_add_f32_e32 v12, 1.0, v12
	v_add_f32_e32 v8, 1.0, v8
	v_rcp_f32_e32 v48, v8
	v_add_f32_e32 v8, v13, v181
	v_mul_f32_e32 v8, 0xbfb8aa3b, v8
	v_exp_f32_e32 v8, v8
	v_exp_f32_e32 v10, v10
	v_rcp_f32_e32 v12, v12
	v_mul_f32_e32 v14, 0xbfb8aa3b, v14
	v_add_f32_e32 v8, 1.0, v8
	v_rcp_f32_e32 v13, v8
	v_add_f32_e32 v8, v9, v147
	v_mul_f32_e32 v8, 0xbfb8aa3b, v8
	v_exp_f32_e32 v8, v8
	v_add_f32_e32 v10, 1.0, v10
	v_rcp_f32_e32 v50, v10
	v_add_f32_e32 v10, v15, v183
	v_add_f32_e32 v8, 1.0, v8
	v_rcp_f32_e32 v49, v8
	v_pk_mul_f32 v[8:9], v[12:13], s[28:29] op_sel_hi:[1,0]
	v_mul_f32_e32 v10, 0xbfb8aa3b, v10
	v_pk_mul_f32 v[12:13], v[104:105], v[8:9]
	v_exp_f32_e32 v10, v10
	v_pk_add_f32 v[52:53], v[12:13], v[12:13]
	v_mul_f32_e32 v8, 0x3fb8aa3b, v12
	v_fmamk_f32 v9, v52, 0x3ab60b61, v195
	v_exp_f32_e32 v8, v8
	v_fmaak_f32 v9, v52, v9, 0x3d2aaaab
	v_fmaak_f32 v9, v52, v9, 0x3e2aaaab
	v_exp_f32_e32 v14, v14
	v_fma_f32 v9, v52, v9, 0.5
	v_add_f32_e32 v10, 1.0, v10
	v_fma_f32 v9, v52, v9, 1.0
	v_rcp_f32_e32 v15, v10
	v_add_f32_e32 v10, v11, v149
	v_mul_f32_e64 v9, v9, -v52
	v_fma_f32 v12, -v8, v8, 1.0
	v_cmp_lt_f32_e64 s[6:7], s84, v52
	v_mul_f32_e32 v10, 0xbfb8aa3b, v10
	v_add_f32_e32 v14, 1.0, v14
	v_cndmask_b32_e64 v9, v12, v9, s[6:7]
	v_exp_f32_e32 v10, v10
	v_sqrt_f32_e32 v12, v9
	v_mul_f32_e32 v9, 0x3fb8aa3b, v13
	v_fmamk_f32 v13, v53, 0x3ab60b61, v195
	v_rcp_f32_e32 v14, v14
	v_exp_f32_e32 v9, v9
	v_fmaak_f32 v13, v53, v13, 0x3d2aaaab
	v_fmaak_f32 v13, v53, v13, 0x3e2aaaab
	v_fma_f32 v13, v53, v13, 0.5
	v_add_f32_e32 v10, 1.0, v10
	v_fma_f32 v13, v53, v13, 1.0
	v_rcp_f32_e32 v51, v10
	v_pk_mul_f32 v[10:11], v[14:15], s[28:29] op_sel_hi:[1,0]
	v_cmp_lt_f32_e32 vcc, s84, v53
	v_mul_f32_e64 v13, v13, -v53
	v_fma_f32 v52, -v9, v9, 1.0
	v_pk_mul_f32 v[14:15], v[106:107], v[10:11]
	v_cndmask_b32_e32 v13, v52, v13, vcc
	v_pk_add_f32 v[52:53], v[14:15], v[14:15]
	v_mul_f32_e32 v10, 0x3fb8aa3b, v14
	v_fmamk_f32 v11, v52, 0x3ab60b61, v195
	v_exp_f32_e32 v10, v10
	v_fmaak_f32 v11, v52, v11, 0x3d2aaaab
	v_fmaak_f32 v11, v52, v11, 0x3e2aaaab
	v_fma_f32 v11, v52, v11, 0.5
	v_fma_f32 v11, v52, v11, 1.0
	v_mul_f32_e64 v11, v11, -v52
	v_fma_f32 v14, -v10, v10, 1.0
	v_cmp_lt_f32_e64 s[6:7], s84, v52
	v_cmp_lt_f32_e32 vcc, s84, v53
	v_sqrt_f32_e32 v13, v13
	v_cndmask_b32_e64 v11, v14, v11, s[6:7]
	v_sqrt_f32_e32 v14, v11
	v_mul_f32_e32 v11, 0x3fb8aa3b, v15
	v_fmamk_f32 v15, v53, 0x3ab60b61, v195
	v_exp_f32_e32 v11, v11
	v_fmaak_f32 v15, v53, v15, 0x3d2aaaab
	v_fmaak_f32 v15, v53, v15, 0x3e2aaaab
	v_fma_f32 v15, v53, v15, 0.5
	v_fma_f32 v15, v53, v15, 1.0
	v_mul_f32_e64 v15, v15, -v53
	v_fma_f32 v52, -v11, v11, 1.0
	v_cndmask_b32_e32 v15, v52, v15, vcc
	v_sqrt_f32_e32 v15, v15
	v_pk_mul_f32 v[12:13], v[48:49], v[12:13]
	v_cmp_gt_u32_e32 vcc, 64, v75
	v_pk_mul_f32 v[12:13], v[12:13], v[62:63]
	v_pk_mul_f32 v[14:15], v[50:51], v[14:15]
	s_nop 0
	v_pk_mul_f32 v[14:15], v[14:15], v[60:61]
	ds_write_b128 v66, v[8:11] offset:8384
	ds_write_b128 v66, v[12:15] offset:24768
	v_and_b32_e32 v8, 63, v74
	v_lshlrev_b32_e32 v9, 2, v8
	v_lshl_or_b32 v9, v76, 12, v9
	v_add_u32_e32 v9, s60, v9
	s_waitcnt lgkmcnt(0)
	s_barrier
	ds_read2st64_b32 v[10:11], v9 offset0:46 offset1:47
	ds_read2st64_b32 v[12:13], v9 offset0:110 offset1:111
	ds_read2st64_b32 v[14:15], v9 offset0:44 offset1:45
	ds_read2st64_b32 v[48:49], v9 offset0:108 offset1:109
	s_waitcnt lgkmcnt(2)
	v_fma_f32 v13, 0, v11, v13
	v_fmac_f32_e32 v12, v13, v10
	v_mul_f32_e32 v10, v11, v10
	s_waitcnt lgkmcnt(0)
	v_fma_f32 v11, v12, v15, v49
	ds_read2st64_b32 v[12:13], v9 offset0:42 offset1:43
	ds_read2st64_b32 v[50:51], v9 offset0:106 offset1:107
	v_fmac_f32_e32 v48, v11, v14
	v_mov_b32_e32 v58, v15
	s_waitcnt lgkmcnt(0)
	v_fma_f32 v11, v48, v13, v51
	ds_read2st64_b32 v[48:49], v9 offset0:40 offset1:41
	ds_read2st64_b32 v[52:53], v9 offset0:104 offset1:105
	v_fmac_f32_e32 v50, v11, v12
	s_waitcnt lgkmcnt(1)
	v_mov_b32_e32 v62, v49
	s_waitcnt lgkmcnt(0)
	v_fma_f32 v11, v50, v49, v53
	ds_read2st64_b32 v[50:51], v9 offset0:38 offset1:39
	ds_read2st64_b32 v[54:55], v9 offset0:102 offset1:103
	v_fmac_f32_e32 v52, v11, v48
	v_mov_b32_e32 v64, v49
	s_waitcnt lgkmcnt(1)
	v_mov_b32_e32 v59, v50
	s_waitcnt lgkmcnt(0)
	v_fmac_f32_e32 v55, v52, v51
	ds_read2st64_b32 v[52:53], v9 offset0:36 offset1:37
	ds_read2st64_b32 v[56:57], v9 offset0:100 offset1:101
	v_mov_b32_e32 v11, v55
	v_mul_f32_e32 v55, v10, v15
	v_mov_b32_e32 v15, v54
	v_pk_fma_f32 v[10:11], v[10:11], v[58:59], v[14:15]
	v_mul_f32_e32 v54, v55, v14
	v_mov_b32_e32 v55, v11
	v_mov_b32_e32 v10, v13
	s_waitcnt lgkmcnt(1)
	v_mov_b32_e32 v11, v53
	v_pk_mul_f32 v[14:15], v[54:55], v[10:11]
	s_waitcnt lgkmcnt(0)
	v_mov_b32_e32 v13, v57
	v_pk_mul_f32 v[14:15], v[14:15], v[12:13]
	v_pk_fma_f32 v[10:11], v[54:55], v[10:11], v[12:13]
	ds_read2st64_b32 v[12:13], v9 offset0:34 offset1:35
	ds_read2st64_b32 v[54:55], v9 offset0:98 offset1:99
	ds_read2st64_b32 v[58:59], v9 offset0:32 offset1:33
	ds_read2st64_b32 v[60:61], v9 offset0:96 offset1:97
	v_mov_b32_e32 v10, v14
	v_mov_b32_e32 v65, v52
	v_pk_mul_f32 v[14:15], v[14:15], v[62:63]
	v_mov_b32_e32 v49, v56
	v_pk_mul_f32 v[14:15], v[14:15], v[48:49]
	v_pk_fma_f32 v[10:11], v[10:11], v[64:65], v[48:49]
	v_and_b32_e32 v57, 0x1fffffc0, v75
	v_mov_b32_e32 v15, v11
	v_mov_b32_e32 v10, v51
	s_waitcnt lgkmcnt(3)
	v_mov_b32_e32 v11, v13
	v_pk_mul_f32 v[48:49], v[14:15], v[10:11]
	s_waitcnt lgkmcnt(2)
	v_mov_b32_e32 v51, v55
	v_pk_mul_f32 v[48:49], v[48:49], v[50:51]
	v_pk_fma_f32 v[10:11], v[14:15], v[10:11], v[50:51]
	v_mov_b32_e32 v14, v53
	v_mov_b32_e32 v10, v48
	v_mov_b32_e32 v50, v53
	v_mov_b32_e32 v51, v12
	v_pk_mul_f32 v[14:15], v[48:49], v[14:15]
	v_mov_b32_e32 v53, v54
	v_pk_mul_f32 v[14:15], v[14:15], v[52:53]
	v_pk_fma_f32 v[10:11], v[10:11], v[50:51], v[52:53]
	v_lshl_add_u32 v9, v8, 3, s60
	v_mov_b32_e32 v15, v11
	v_mov_b32_e32 v10, v13
	s_waitcnt lgkmcnt(1)
	v_mov_b32_e32 v11, v59
	v_pk_mul_f32 v[48:49], v[14:15], v[10:11]
	s_waitcnt lgkmcnt(0)
	v_mov_b32_e32 v13, v61
	v_pk_mul_f32 v[48:49], v[48:49], v[12:13]
	v_pk_fma_f32 v[10:11], v[14:15], v[10:11], v[12:13]
	v_mov_b32_e32 v12, v59
	v_mov_b32_e32 v10, v48
	v_mov_b32_e32 v14, v59
	v_mov_b32_e32 v15, v58
	v_pk_mul_f32 v[12:13], v[48:49], v[12:13]
	v_mov_b32_e32 v59, v60
	v_pk_mul_f32 v[12:13], v[12:13], v[58:59]
	v_pk_fma_f32 v[10:11], v[10:11], v[14:15], v[58:59]
	v_lshl_add_u32 v57, v57, 3, v9
	v_mov_b32_e32 v13, v11
	ds_write_b64 v57, v[12:13] offset:40960
	s_waitcnt lgkmcnt(0)
	s_barrier
	s_and_saveexec_b64 s[6:7], vcc
	s_cbranch_execz .LBB0_382
	s_lshl_b32 s26, s26, 7
	ds_read_b64 v[14:15], v9 offset:42496
	v_lshl_or_b32 v10, v74, 3, v196
	s_or_b32 s25, s26, s25
	v_add_u32_e32 v10, s60, v10
	s_or_b32 s26, s25, 64
	ds_read_b64 v[48:49], v10 offset:42496
	ds_read2st64_b64 v[10:13], v9 offset0:80 offset1:81
	s_ashr_i32 s27, s26, 31
	s_lshl_b64 s[26:27], s[26:27], 12
	s_mov_b64 s[28:29], s[74:75]
	s_add_u32 s25, s28, s26
	s_waitcnt lgkmcnt(2)
	v_fma_f32 v9, 0, v14, v15
	s_addc_u32 s27, s29, s27
	s_lshl_b32 s26, s23, 3
	s_waitcnt lgkmcnt(1)
	v_fmac_f32_e32 v49, v9, v48
	s_add_u32 s26, s25, s26
	v_mul_f32_e32 v14, v14, v48
	s_waitcnt lgkmcnt(0)
	v_fma_f32 v15, v49, v12, v13
	v_mov_b32_e32 v13, v10
	s_addc_u32 s27, s27, 0
	v_lshlrev_b32_e32 v144, 3, v8
	v_pk_mul_f32 v[48:49], v[14:15], v[12:13]
	v_lshl_add_u64 v[8:9], s[26:27], 0, v[144:145]
	v_pk_mul_f32 v[48:49], v[48:49], v[10:11]
	v_pk_fma_f32 v[10:11], v[14:15], v[12:13], v[10:11]
	v_add_co_u32_e32 v8, vcc, 0x115e0000, v8
	v_mov_b32_e32 v49, v11
	s_nop 0
	v_addc_co_u32_e32 v9, vcc, 0, v9, vcc
	flat_store_dwordx2 v[8:9], v[48:49]
	s_branch .LBB0_382
